# P8 cross attention rewritten by hand: all 256 scores in registers, single pass per 256-query tile, bf16 MFMA 32x32x16, K streamed via LDS, dwordx4 output stores
# speedup vs baseline: 1.1124x; 1.0231x over previous
.LBB0_1190:
	s_or_b64 exec, exec, s[10:11]
	s_add_u32 s14, s38, 0x1bf00000
	s_addc_u32 s15, s39, 0
	s_add_u32 s12, s38, 0x6e00000
	s_addc_u32 s13, s39, 0
	v_mov_b32_e32 v171, v206
	s_add_u32 s18, s38, 0x8600000
	s_waitcnt lgkmcnt(0)
	s_barrier
	s_addc_u32 s19, s39, 0
	v_and_b32_e32 v0, 63, v171
	s_ashr_i32 s42, s2, 1
	v_readfirstlane_b32 s35, v171
	s_cmpk_gt_i32 s42, 0x7f
	v_lshlrev_b32_e32 v211, 1, v171
	v_lshlrev_b32_e32 v212, 2, v171
	v_and_b32_e32 v213, 4, v171
	v_and_b32_e32 v175, 31, v171
	v_lshrrev_b32_e32 v210, 5, v0
	v_ashrrev_i32_e32 v168, 5, v171
	v_and_b32_e32 v200, 63, v206
	v_and_b32_e32 v250, 31, v206
	v_lshrrev_b32_e32 v251, 5, v200
	v_lshrrev_b32_e32 v201, 6, v206
	v_mov_b32_e32 v252, 0x210
	v_mul_u32_u24_e32 v196, v250, v252
	v_lshl_add_u32 v196, v251, 4, v196
	v_add_u32_e32 v192, 0x21000, v196
	v_add_u32_e32 v197, 0x10800, v196
	v_lshrrev_b32_e32 v200, 5, v206
	v_mul_u32_u24_e32 v193, v200, v252
	v_lshl_add_u32 v193, v250, 4, v193
	v_add_u32_e32 v193, 0x21000, v193
	v_lshlrev_b32_e32 v194, 11, v200
	v_lshl_add_u32 v194, v250, 4, v194
	v_and_b32_e32 v200, 0x7f, v206
	v_lshrrev_b32_e32 v253, 7, v206
	v_lshlrev_b32_e32 v202, 12, v200
	v_lshl_add_u32 v202, v253, 4, v202
	v_lshlrev_b32_e32 v200, 1, v200
	v_and_b32_e32 v203, 0xf0, v200
	v_and_b32_e32 v252, 3, v200
	v_or_b32_e32 v203, v203, v252
	v_and_b32_e32 v252, 4, v200
	v_lshl_or_b32 v203, v252, 1, v203
	v_and_b32_e32 v252, 8, v200
	v_lshrrev_b32_e32 v252, 1, v252
	v_or_b32_e32 v203, v203, v252
	v_lshlrev_b32_e32 v203, 1, v203
	v_mov_b32_e32 v252, 0x1080
	v_mul_u32_u24_e32 v252, v253, v252
	v_add_u32_e32 v203, v203, v252
	v_add_u32_e32 v204, 0x10800, v203
	s_lshr_b32 s10, s2, 1
	s_lshr_b32 s11, s10, 2
	s_and_b32 s12, s10, 3
	s_lshl_b32 s13, s12, 9
	s_and_b32 s18, s2, 1
	s_lshl_b32 s18, s18, 10
	s_lshl_b32 s19, s11, 11
	s_add_u32 s18, s18, s19
	s_lshl_b32 s19, s11, 8
	s_mov_b32 s58, 4
	s_mov_b32 s59, 0
	v_lshl_add_u32 v201, v201, 5, v250
	v_lshlrev_b32_e32 v195, 11, v201
	v_lshl_add_u32 v195, v251, 4, v195
	s_mov_b64 s[62:63], -1
.Lxa_unit:
	s_lshr_b32 s20, s18, 21
	s_lshl_b32 s21, s18, 11
	s_add_u32 s21, s21, s13
	s_addc_u32 s20, s20, 0
	s_add_u32 s50, s38, s21
	s_addc_u32 s51, s39, s20
	s_add_u32 s52, s50, 0x1bf00000
	s_addc_u32 s53, s51, 0
	s_add_u32 s50, s50, 0x11f00000
	s_addc_u32 s51, s51, 0
	s_lshl_b32 s21, s19, 11
	s_add_u32 s21, s21, s13
	s_add_u32 s54, s38, s21
	s_addc_u32 s55, s39, 0
	s_add_u32 s56, s54, 0x8600000
	s_addc_u32 s57, s55, 0
	s_add_u32 s54, s54, 0x6e00000
	s_addc_u32 s55, s55, 0
	s_add_u32 s76, s50, 0x80000
	s_addc_u32 s77, s51, 0
	s_add_u32 s72, s54, 0x8000
	s_addc_u32 s73, s55, 0
	global_load_dwordx4 v[234:237], v194, s[54:55]
	global_load_dwordx4 v[238:241], v194, s[72:73]
	s_add_u32 s70, s54, 0x10000
	s_addc_u32 s71, s55, 0
	s_add_u32 s72, s54, 0x18000
	s_addc_u32 s73, s55, 0
	global_load_dwordx4 v[242:245], v194, s[70:71]
	global_load_dwordx4 v[246:249], v194, s[72:73]
	global_load_dwordx4 v[0:3], v195, s[50:51]
	global_load_dwordx4 v[4:7], v195, s[50:51] offset:32
	global_load_dwordx4 v[8:11], v195, s[50:51] offset:64
	global_load_dwordx4 v[12:15], v195, s[50:51] offset:96
	global_load_dwordx4 v[16:19], v195, s[50:51] offset:128
	global_load_dwordx4 v[20:23], v195, s[50:51] offset:160
	global_load_dwordx4 v[24:27], v195, s[50:51] offset:192
	global_load_dwordx4 v[28:31], v195, s[50:51] offset:224
	global_load_dwordx4 v[32:35], v195, s[50:51] offset:256
	global_load_dwordx4 v[36:39], v195, s[50:51] offset:288
	global_load_dwordx4 v[40:43], v195, s[50:51] offset:320
	global_load_dwordx4 v[44:47], v195, s[50:51] offset:352
	global_load_dwordx4 v[48:51], v195, s[50:51] offset:384
	global_load_dwordx4 v[52:55], v195, s[50:51] offset:416
	global_load_dwordx4 v[56:59], v195, s[50:51] offset:448
	global_load_dwordx4 v[60:63], v195, s[50:51] offset:480
	s_barrier
	global_load_dwordx4 v[64:67], v202, s[56:57]
	global_load_dwordx4 v[68:71], v202, s[56:57] offset:2048
	global_load_dwordx4 v[72:75], v202, s[56:57] offset:64
	global_load_dwordx4 v[76:79], v202, s[56:57] offset:2112
	global_load_dwordx4 v[80:83], v202, s[56:57] offset:128
	global_load_dwordx4 v[84:87], v202, s[56:57] offset:2176
	global_load_dwordx4 v[88:91], v202, s[56:57] offset:192
	global_load_dwordx4 v[92:95], v202, s[56:57] offset:2240
	global_load_dwordx4 v[96:99], v202, s[56:57] offset:256
	global_load_dwordx4 v[100:103], v202, s[56:57] offset:2304
	global_load_dwordx4 v[104:107], v202, s[56:57] offset:320
	global_load_dwordx4 v[108:111], v202, s[56:57] offset:2368
	global_load_dwordx4 v[112:115], v202, s[56:57] offset:384
	global_load_dwordx4 v[116:119], v202, s[56:57] offset:2432
	global_load_dwordx4 v[120:123], v202, s[56:57] offset:448
	global_load_dwordx4 v[124:127], v202, s[56:57] offset:2496
	s_mov_b32 s21, 0xffff0000
	s_waitcnt vmcnt(14)
	v_and_b32_e32 v200, 0xffff, v64
	v_lshl_or_b32 v200, v68, 16, v200
	v_lshrrev_b32_e32 v201, 16, v64
	v_and_or_b32 v201, v68, s21, v201
	ds_write_b32 v203, v200
	ds_write_b32 v203, v201 offset:528
	v_and_b32_e32 v200, 0xffff, v65
	v_lshl_or_b32 v200, v69, 16, v200
	v_lshrrev_b32_e32 v201, 16, v65
	v_and_or_b32 v201, v69, s21, v201
	ds_write_b32 v203, v200 offset:1056
	ds_write_b32 v203, v201 offset:1584
	v_and_b32_e32 v200, 0xffff, v66
	v_lshl_or_b32 v200, v70, 16, v200
	v_lshrrev_b32_e32 v201, 16, v66
	v_and_or_b32 v201, v70, s21, v201
	ds_write_b32 v203, v200 offset:2112
	ds_write_b32 v203, v201 offset:2640
	v_and_b32_e32 v200, 0xffff, v67
	v_lshl_or_b32 v200, v71, 16, v200
	v_lshrrev_b32_e32 v201, 16, v67
	v_and_or_b32 v201, v71, s21, v201
	ds_write_b32 v203, v200 offset:3168
	ds_write_b32 v203, v201 offset:3696
	s_waitcnt vmcnt(12)
	v_and_b32_e32 v200, 0xffff, v72
	v_lshl_or_b32 v200, v76, 16, v200
	v_lshrrev_b32_e32 v201, 16, v72
	v_and_or_b32 v201, v76, s21, v201
	ds_write_b32 v203, v200 offset:16896
	ds_write_b32 v203, v201 offset:17424
	v_and_b32_e32 v200, 0xffff, v73
	v_lshl_or_b32 v200, v77, 16, v200
	v_lshrrev_b32_e32 v201, 16, v73
	v_and_or_b32 v201, v77, s21, v201
	ds_write_b32 v203, v200 offset:17952
	ds_write_b32 v203, v201 offset:18480
	v_and_b32_e32 v200, 0xffff, v74
	v_lshl_or_b32 v200, v78, 16, v200
	v_lshrrev_b32_e32 v201, 16, v74
	v_and_or_b32 v201, v78, s21, v201
	ds_write_b32 v203, v200 offset:19008
	ds_write_b32 v203, v201 offset:19536
	v_and_b32_e32 v200, 0xffff, v75
	v_lshl_or_b32 v200, v79, 16, v200
	v_lshrrev_b32_e32 v201, 16, v75
	v_and_or_b32 v201, v79, s21, v201
	ds_write_b32 v203, v200 offset:20064
	ds_write_b32 v203, v201 offset:20592
	s_waitcnt vmcnt(10)
	v_and_b32_e32 v200, 0xffff, v80
	v_lshl_or_b32 v200, v84, 16, v200
	v_lshrrev_b32_e32 v201, 16, v80
	v_and_or_b32 v201, v84, s21, v201
	ds_write_b32 v203, v200 offset:33792
	ds_write_b32 v203, v201 offset:34320
	v_and_b32_e32 v200, 0xffff, v81
	v_lshl_or_b32 v200, v85, 16, v200
	v_lshrrev_b32_e32 v201, 16, v81
	v_and_or_b32 v201, v85, s21, v201
	ds_write_b32 v203, v200 offset:34848
	ds_write_b32 v203, v201 offset:35376
	v_and_b32_e32 v200, 0xffff, v82
	v_lshl_or_b32 v200, v86, 16, v200
	v_lshrrev_b32_e32 v201, 16, v82
	v_and_or_b32 v201, v86, s21, v201
	ds_write_b32 v203, v200 offset:35904
	ds_write_b32 v203, v201 offset:36432
	v_and_b32_e32 v200, 0xffff, v83
	v_lshl_or_b32 v200, v87, 16, v200
	v_lshrrev_b32_e32 v201, 16, v83
	v_and_or_b32 v201, v87, s21, v201
	ds_write_b32 v203, v200 offset:36960
	ds_write_b32 v203, v201 offset:37488
	s_waitcnt vmcnt(8)
	v_and_b32_e32 v200, 0xffff, v88
	v_lshl_or_b32 v200, v92, 16, v200
	v_lshrrev_b32_e32 v201, 16, v88
	v_and_or_b32 v201, v92, s21, v201
	ds_write_b32 v203, v200 offset:50688
	ds_write_b32 v203, v201 offset:51216
	v_and_b32_e32 v200, 0xffff, v89
	v_lshl_or_b32 v200, v93, 16, v200
	v_lshrrev_b32_e32 v201, 16, v89
	v_and_or_b32 v201, v93, s21, v201
	ds_write_b32 v203, v200 offset:51744
	ds_write_b32 v203, v201 offset:52272
	v_and_b32_e32 v200, 0xffff, v90
	v_lshl_or_b32 v200, v94, 16, v200
	v_lshrrev_b32_e32 v201, 16, v90
	v_and_or_b32 v201, v94, s21, v201
	ds_write_b32 v203, v200 offset:52800
	ds_write_b32 v203, v201 offset:53328
	v_and_b32_e32 v200, 0xffff, v91
	v_lshl_or_b32 v200, v95, 16, v200
	v_lshrrev_b32_e32 v201, 16, v91
	v_and_or_b32 v201, v95, s21, v201
	ds_write_b32 v203, v200 offset:53856
	ds_write_b32 v203, v201 offset:54384
	s_waitcnt vmcnt(6)
	v_and_b32_e32 v200, 0xffff, v96
	v_lshl_or_b32 v200, v100, 16, v200
	v_lshrrev_b32_e32 v201, 16, v96
	v_and_or_b32 v201, v100, s21, v201
	ds_write_b32 v204, v200
	ds_write_b32 v204, v201 offset:528
	v_and_b32_e32 v200, 0xffff, v97
	v_lshl_or_b32 v200, v101, 16, v200
	v_lshrrev_b32_e32 v201, 16, v97
	v_and_or_b32 v201, v101, s21, v201
	ds_write_b32 v204, v200 offset:1056
	ds_write_b32 v204, v201 offset:1584
	v_and_b32_e32 v200, 0xffff, v98
	v_lshl_or_b32 v200, v102, 16, v200
	v_lshrrev_b32_e32 v201, 16, v98
	v_and_or_b32 v201, v102, s21, v201
	ds_write_b32 v204, v200 offset:2112
	ds_write_b32 v204, v201 offset:2640
	v_and_b32_e32 v200, 0xffff, v99
	v_lshl_or_b32 v200, v103, 16, v200
	v_lshrrev_b32_e32 v201, 16, v99
	v_and_or_b32 v201, v103, s21, v201
	ds_write_b32 v204, v200 offset:3168
	ds_write_b32 v204, v201 offset:3696
	s_waitcnt vmcnt(4)
	v_and_b32_e32 v200, 0xffff, v104
	v_lshl_or_b32 v200, v108, 16, v200
	v_lshrrev_b32_e32 v201, 16, v104
	v_and_or_b32 v201, v108, s21, v201
	ds_write_b32 v204, v200 offset:16896
	ds_write_b32 v204, v201 offset:17424
	v_and_b32_e32 v200, 0xffff, v105
	v_lshl_or_b32 v200, v109, 16, v200
	v_lshrrev_b32_e32 v201, 16, v105
	v_and_or_b32 v201, v109, s21, v201
	ds_write_b32 v204, v200 offset:17952
	ds_write_b32 v204, v201 offset:18480
	v_and_b32_e32 v200, 0xffff, v106
	v_lshl_or_b32 v200, v110, 16, v200
	v_lshrrev_b32_e32 v201, 16, v106
	v_and_or_b32 v201, v110, s21, v201
	ds_write_b32 v204, v200 offset:19008
	ds_write_b32 v204, v201 offset:19536
	v_and_b32_e32 v200, 0xffff, v107
	v_lshl_or_b32 v200, v111, 16, v200
	v_lshrrev_b32_e32 v201, 16, v107
	v_and_or_b32 v201, v111, s21, v201
	ds_write_b32 v204, v200 offset:20064
	ds_write_b32 v204, v201 offset:20592
	s_waitcnt vmcnt(2)
	v_and_b32_e32 v200, 0xffff, v112
	v_lshl_or_b32 v200, v116, 16, v200
	v_lshrrev_b32_e32 v201, 16, v112
	v_and_or_b32 v201, v116, s21, v201
	ds_write_b32 v204, v200 offset:33792
	ds_write_b32 v204, v201 offset:34320
	v_and_b32_e32 v200, 0xffff, v113
	v_lshl_or_b32 v200, v117, 16, v200
	v_lshrrev_b32_e32 v201, 16, v113
	v_and_or_b32 v201, v117, s21, v201
	ds_write_b32 v204, v200 offset:34848
	ds_write_b32 v204, v201 offset:35376
	v_and_b32_e32 v200, 0xffff, v114
	v_lshl_or_b32 v200, v118, 16, v200
	v_lshrrev_b32_e32 v201, 16, v114
	v_and_or_b32 v201, v118, s21, v201
	ds_write_b32 v204, v200 offset:35904
	ds_write_b32 v204, v201 offset:36432
	v_and_b32_e32 v200, 0xffff, v115
	v_lshl_or_b32 v200, v119, 16, v200
	v_lshrrev_b32_e32 v201, 16, v115
	v_and_or_b32 v201, v119, s21, v201
	ds_write_b32 v204, v200 offset:36960
	ds_write_b32 v204, v201 offset:37488
	s_waitcnt vmcnt(0)
	v_and_b32_e32 v200, 0xffff, v120
	v_lshl_or_b32 v200, v124, 16, v200
	v_lshrrev_b32_e32 v201, 16, v120
	v_and_or_b32 v201, v124, s21, v201
	ds_write_b32 v204, v200 offset:50688
	ds_write_b32 v204, v201 offset:51216
	v_and_b32_e32 v200, 0xffff, v121
	v_lshl_or_b32 v200, v125, 16, v200
	v_lshrrev_b32_e32 v201, 16, v121
	v_and_or_b32 v201, v125, s21, v201
	ds_write_b32 v204, v200 offset:51744
	ds_write_b32 v204, v201 offset:52272
	v_and_b32_e32 v200, 0xffff, v122
	v_lshl_or_b32 v200, v126, 16, v200
	v_lshrrev_b32_e32 v201, 16, v122
	v_and_or_b32 v201, v126, s21, v201
	ds_write_b32 v204, v200 offset:52800
	ds_write_b32 v204, v201 offset:53328
	v_and_b32_e32 v200, 0xffff, v123
	v_lshl_or_b32 v200, v127, 16, v200
	v_lshrrev_b32_e32 v201, 16, v123
	v_and_or_b32 v201, v127, s21, v201
	ds_write_b32 v204, v200 offset:53856
	ds_write_b32 v204, v201 offset:54384
	s_waitcnt vmcnt(0) lgkmcnt(0)
	s_barrier
.Lxa_tile:
	s_waitcnt vmcnt(34)
	s_barrier
	ds_write_b128 v193, v[234:237]
	ds_write_b128 v193, v[238:241] offset:8448
	s_add_u32 s70, s54, 0x20000
	s_addc_u32 s71, s55, 0
	s_add_u32 s72, s54, 0x28000
	s_addc_u32 s73, s55, 0
	global_load_dwordx4 v[234:237], v194, s[70:71]
	global_load_dwordx4 v[238:241], v194, s[72:73]
	s_waitcnt lgkmcnt(0)
	s_barrier
	ds_read_b128 v[210:213], v192
	ds_read_b128 v[214:217], v192 offset:32
	ds_read_b128 v[218:221], v192 offset:64
	ds_read_b128 v[222:225], v192 offset:96
	ds_read_b128 v[226:229], v192 offset:128
	ds_read_b128 v[230:233], v192 offset:160
	s_waitcnt vmcnt(18)
	s_waitcnt lgkmcnt(5)
	v_mfma_f32_32x32x16_bf16 v[64:79], v[210:213], v[0:3], 0
	ds_read_b128 v[210:213], v192 offset:192
	s_waitcnt lgkmcnt(5)
	v_mfma_f32_32x32x16_bf16 v[64:79], v[214:217], v[4:7], v[64:79]
	ds_read_b128 v[214:217], v192 offset:224
	s_waitcnt lgkmcnt(5)
	v_mfma_f32_32x32x16_bf16 v[64:79], v[218:221], v[8:11], v[64:79]
	ds_read_b128 v[218:221], v192 offset:256
	s_waitcnt lgkmcnt(5)
	v_mfma_f32_32x32x16_bf16 v[64:79], v[222:225], v[12:15], v[64:79]
	ds_read_b128 v[222:225], v192 offset:288
	s_waitcnt lgkmcnt(5)
	v_mfma_f32_32x32x16_bf16 v[64:79], v[226:229], v[16:19], v[64:79]
	ds_read_b128 v[226:229], v192 offset:320
	s_waitcnt lgkmcnt(5)
	v_mfma_f32_32x32x16_bf16 v[64:79], v[230:233], v[20:23], v[64:79]
	ds_read_b128 v[230:233], v192 offset:352
	s_waitcnt lgkmcnt(5)
	v_mfma_f32_32x32x16_bf16 v[64:79], v[210:213], v[24:27], v[64:79]
	ds_read_b128 v[210:213], v192 offset:384
	s_waitcnt lgkmcnt(5)
	v_mfma_f32_32x32x16_bf16 v[64:79], v[214:217], v[28:31], v[64:79]
	ds_read_b128 v[214:217], v192 offset:416
	s_waitcnt lgkmcnt(5)
	v_mfma_f32_32x32x16_bf16 v[64:79], v[218:221], v[32:35], v[64:79]
	ds_read_b128 v[218:221], v192 offset:448
	s_waitcnt lgkmcnt(5)
	v_mfma_f32_32x32x16_bf16 v[64:79], v[222:225], v[36:39], v[64:79]
	ds_read_b128 v[222:225], v192 offset:480
	s_waitcnt lgkmcnt(5)
	v_mfma_f32_32x32x16_bf16 v[64:79], v[226:229], v[40:43], v[64:79]
	s_waitcnt lgkmcnt(4)
	v_mfma_f32_32x32x16_bf16 v[64:79], v[230:233], v[44:47], v[64:79]
	s_waitcnt lgkmcnt(3)
	v_mfma_f32_32x32x16_bf16 v[64:79], v[210:213], v[48:51], v[64:79]
	s_waitcnt lgkmcnt(2)
	v_mfma_f32_32x32x16_bf16 v[64:79], v[214:217], v[52:55], v[64:79]
	s_waitcnt lgkmcnt(1)
	v_mfma_f32_32x32x16_bf16 v[64:79], v[218:221], v[56:59], v[64:79]
	s_waitcnt lgkmcnt(0)
	v_mfma_f32_32x32x16_bf16 v[64:79], v[222:225], v[60:63], v[64:79]
	s_waitcnt vmcnt(34)
	s_barrier
	ds_write_b128 v193, v[242:245]
	ds_write_b128 v193, v[246:249] offset:8448
	s_add_u32 s70, s54, 0x30000
	s_addc_u32 s71, s55, 0
	s_add_u32 s72, s54, 0x38000
	s_addc_u32 s73, s55, 0
	global_load_dwordx4 v[242:245], v194, s[70:71]
	global_load_dwordx4 v[246:249], v194, s[72:73]
	s_waitcnt lgkmcnt(0)
	s_barrier
	ds_read_b128 v[210:213], v192
	ds_read_b128 v[214:217], v192 offset:32
	ds_read_b128 v[218:221], v192 offset:64
	ds_read_b128 v[222:225], v192 offset:96
	ds_read_b128 v[226:229], v192 offset:128
	ds_read_b128 v[230:233], v192 offset:160
	s_waitcnt lgkmcnt(5)
	v_mfma_f32_32x32x16_bf16 v[80:95], v[210:213], v[0:3], 0
	ds_read_b128 v[210:213], v192 offset:192
	s_waitcnt lgkmcnt(5)
	v_mfma_f32_32x32x16_bf16 v[80:95], v[214:217], v[4:7], v[80:95]
	ds_read_b128 v[214:217], v192 offset:224
	s_waitcnt lgkmcnt(5)
	v_mfma_f32_32x32x16_bf16 v[80:95], v[218:221], v[8:11], v[80:95]
	ds_read_b128 v[218:221], v192 offset:256
	s_waitcnt lgkmcnt(5)
	v_mfma_f32_32x32x16_bf16 v[80:95], v[222:225], v[12:15], v[80:95]
	ds_read_b128 v[222:225], v192 offset:288
	s_waitcnt lgkmcnt(5)
	v_mfma_f32_32x32x16_bf16 v[80:95], v[226:229], v[16:19], v[80:95]
	ds_read_b128 v[226:229], v192 offset:320
	s_waitcnt lgkmcnt(5)
	v_mfma_f32_32x32x16_bf16 v[80:95], v[230:233], v[20:23], v[80:95]
	ds_read_b128 v[230:233], v192 offset:352
	s_waitcnt lgkmcnt(5)
	v_mfma_f32_32x32x16_bf16 v[80:95], v[210:213], v[24:27], v[80:95]
	ds_read_b128 v[210:213], v192 offset:384
	s_waitcnt lgkmcnt(5)
	v_mfma_f32_32x32x16_bf16 v[80:95], v[214:217], v[28:31], v[80:95]
	ds_read_b128 v[214:217], v192 offset:416
	s_waitcnt lgkmcnt(5)
	v_mfma_f32_32x32x16_bf16 v[80:95], v[218:221], v[32:35], v[80:95]
	ds_read_b128 v[218:221], v192 offset:448
	s_waitcnt lgkmcnt(5)
	v_mfma_f32_32x32x16_bf16 v[80:95], v[222:225], v[36:39], v[80:95]
	ds_read_b128 v[222:225], v192 offset:480
	s_waitcnt lgkmcnt(5)
	v_mfma_f32_32x32x16_bf16 v[80:95], v[226:229], v[40:43], v[80:95]
	s_waitcnt lgkmcnt(4)
	v_mfma_f32_32x32x16_bf16 v[80:95], v[230:233], v[44:47], v[80:95]
	s_waitcnt lgkmcnt(3)
	v_mfma_f32_32x32x16_bf16 v[80:95], v[210:213], v[48:51], v[80:95]
	s_waitcnt lgkmcnt(2)
	v_mfma_f32_32x32x16_bf16 v[80:95], v[214:217], v[52:55], v[80:95]
	s_waitcnt lgkmcnt(1)
	v_mfma_f32_32x32x16_bf16 v[80:95], v[218:221], v[56:59], v[80:95]
	s_waitcnt lgkmcnt(0)
	v_mfma_f32_32x32x16_bf16 v[80:95], v[222:225], v[60:63], v[80:95]
	s_waitcnt vmcnt(2)
	s_barrier
	ds_write_b128 v193, v[234:237]
	ds_write_b128 v193, v[238:241] offset:8448
	s_add_u32 s70, s54, 0x40000
	s_addc_u32 s71, s55, 0
	s_add_u32 s72, s54, 0x48000
	s_addc_u32 s73, s55, 0
	global_load_dwordx4 v[234:237], v194, s[70:71]
	global_load_dwordx4 v[238:241], v194, s[72:73]
	s_waitcnt lgkmcnt(0)
	s_barrier
	ds_read_b128 v[210:213], v192
	ds_read_b128 v[214:217], v192 offset:32
	ds_read_b128 v[218:221], v192 offset:64
	ds_read_b128 v[222:225], v192 offset:96
	ds_read_b128 v[226:229], v192 offset:128
	ds_read_b128 v[230:233], v192 offset:160
	s_waitcnt lgkmcnt(5)
	v_mfma_f32_32x32x16_bf16 v[96:111], v[210:213], v[0:3], 0
	ds_read_b128 v[210:213], v192 offset:192
	s_waitcnt lgkmcnt(5)
	v_mfma_f32_32x32x16_bf16 v[96:111], v[214:217], v[4:7], v[96:111]
	ds_read_b128 v[214:217], v192 offset:224
	s_waitcnt lgkmcnt(5)
	v_mfma_f32_32x32x16_bf16 v[96:111], v[218:221], v[8:11], v[96:111]
	ds_read_b128 v[218:221], v192 offset:256
	s_waitcnt lgkmcnt(5)
	v_mfma_f32_32x32x16_bf16 v[96:111], v[222:225], v[12:15], v[96:111]
	ds_read_b128 v[222:225], v192 offset:288
	s_waitcnt lgkmcnt(5)
	v_mfma_f32_32x32x16_bf16 v[96:111], v[226:229], v[16:19], v[96:111]
	ds_read_b128 v[226:229], v192 offset:320
	s_waitcnt lgkmcnt(5)
	v_mfma_f32_32x32x16_bf16 v[96:111], v[230:233], v[20:23], v[96:111]
	ds_read_b128 v[230:233], v192 offset:352
	s_waitcnt lgkmcnt(5)
	v_mfma_f32_32x32x16_bf16 v[96:111], v[210:213], v[24:27], v[96:111]
	ds_read_b128 v[210:213], v192 offset:384
	s_waitcnt lgkmcnt(5)
	v_mfma_f32_32x32x16_bf16 v[96:111], v[214:217], v[28:31], v[96:111]
	ds_read_b128 v[214:217], v192 offset:416
	s_waitcnt lgkmcnt(5)
	v_mfma_f32_32x32x16_bf16 v[96:111], v[218:221], v[32:35], v[96:111]
	ds_read_b128 v[218:221], v192 offset:448
	s_waitcnt lgkmcnt(5)
	v_mfma_f32_32x32x16_bf16 v[96:111], v[222:225], v[36:39], v[96:111]
	ds_read_b128 v[222:225], v192 offset:480
	s_waitcnt lgkmcnt(5)
	v_mfma_f32_32x32x16_bf16 v[96:111], v[226:229], v[40:43], v[96:111]
	s_waitcnt lgkmcnt(4)
	v_mfma_f32_32x32x16_bf16 v[96:111], v[230:233], v[44:47], v[96:111]
	s_waitcnt lgkmcnt(3)
	v_mfma_f32_32x32x16_bf16 v[96:111], v[210:213], v[48:51], v[96:111]
	s_waitcnt lgkmcnt(2)
	v_mfma_f32_32x32x16_bf16 v[96:111], v[214:217], v[52:55], v[96:111]
	s_waitcnt lgkmcnt(1)
	v_mfma_f32_32x32x16_bf16 v[96:111], v[218:221], v[56:59], v[96:111]
	s_waitcnt lgkmcnt(0)
	v_mfma_f32_32x32x16_bf16 v[96:111], v[222:225], v[60:63], v[96:111]
	s_waitcnt vmcnt(2)
	s_barrier
	ds_write_b128 v193, v[242:245]
	ds_write_b128 v193, v[246:249] offset:8448
	s_add_u32 s70, s54, 0x50000
	s_addc_u32 s71, s55, 0
	s_add_u32 s72, s54, 0x58000
	s_addc_u32 s73, s55, 0
	global_load_dwordx4 v[242:245], v194, s[70:71]
	global_load_dwordx4 v[246:249], v194, s[72:73]
	s_waitcnt lgkmcnt(0)
	s_barrier
	ds_read_b128 v[210:213], v192
	ds_read_b128 v[214:217], v192 offset:32
	ds_read_b128 v[218:221], v192 offset:64
	ds_read_b128 v[222:225], v192 offset:96
	ds_read_b128 v[226:229], v192 offset:128
	ds_read_b128 v[230:233], v192 offset:160
	s_waitcnt lgkmcnt(5)
	v_mfma_f32_32x32x16_bf16 v[112:127], v[210:213], v[0:3], 0
	ds_read_b128 v[210:213], v192 offset:192
	s_waitcnt lgkmcnt(5)
	v_mfma_f32_32x32x16_bf16 v[112:127], v[214:217], v[4:7], v[112:127]
	ds_read_b128 v[214:217], v192 offset:224
	s_waitcnt lgkmcnt(5)
	v_mfma_f32_32x32x16_bf16 v[112:127], v[218:221], v[8:11], v[112:127]
	ds_read_b128 v[218:221], v192 offset:256
	s_waitcnt lgkmcnt(5)
	v_mfma_f32_32x32x16_bf16 v[112:127], v[222:225], v[12:15], v[112:127]
	ds_read_b128 v[222:225], v192 offset:288
	s_waitcnt lgkmcnt(5)
	v_mfma_f32_32x32x16_bf16 v[112:127], v[226:229], v[16:19], v[112:127]
	ds_read_b128 v[226:229], v192 offset:320
	s_waitcnt lgkmcnt(5)
	v_mfma_f32_32x32x16_bf16 v[112:127], v[230:233], v[20:23], v[112:127]
	ds_read_b128 v[230:233], v192 offset:352
	s_waitcnt lgkmcnt(5)
	v_mfma_f32_32x32x16_bf16 v[112:127], v[210:213], v[24:27], v[112:127]
	ds_read_b128 v[210:213], v192 offset:384
	s_waitcnt lgkmcnt(5)
	v_mfma_f32_32x32x16_bf16 v[112:127], v[214:217], v[28:31], v[112:127]
	ds_read_b128 v[214:217], v192 offset:416
	s_waitcnt lgkmcnt(5)
	v_mfma_f32_32x32x16_bf16 v[112:127], v[218:221], v[32:35], v[112:127]
	ds_read_b128 v[218:221], v192 offset:448
	s_waitcnt lgkmcnt(5)
	v_mfma_f32_32x32x16_bf16 v[112:127], v[222:225], v[36:39], v[112:127]
	ds_read_b128 v[222:225], v192 offset:480
	s_waitcnt lgkmcnt(5)
	v_mfma_f32_32x32x16_bf16 v[112:127], v[226:229], v[40:43], v[112:127]
	s_waitcnt lgkmcnt(4)
	v_mfma_f32_32x32x16_bf16 v[112:127], v[230:233], v[44:47], v[112:127]
	s_waitcnt lgkmcnt(3)
	v_mfma_f32_32x32x16_bf16 v[112:127], v[210:213], v[48:51], v[112:127]
	s_waitcnt lgkmcnt(2)
	v_mfma_f32_32x32x16_bf16 v[112:127], v[214:217], v[52:55], v[112:127]
	s_waitcnt lgkmcnt(1)
	v_mfma_f32_32x32x16_bf16 v[112:127], v[218:221], v[56:59], v[112:127]
	s_waitcnt lgkmcnt(0)
	v_mfma_f32_32x32x16_bf16 v[112:127], v[222:225], v[60:63], v[112:127]
	s_waitcnt vmcnt(2)
	s_barrier
	ds_write_b128 v193, v[234:237]
	ds_write_b128 v193, v[238:241] offset:8448
	s_add_u32 s70, s54, 0x60000
	s_addc_u32 s71, s55, 0
	s_add_u32 s72, s54, 0x68000
	s_addc_u32 s73, s55, 0
	global_load_dwordx4 v[234:237], v194, s[70:71]
	global_load_dwordx4 v[238:241], v194, s[72:73]
	s_waitcnt lgkmcnt(0)
	s_barrier
	ds_read_b128 v[210:213], v192
	ds_read_b128 v[214:217], v192 offset:32
	ds_read_b128 v[218:221], v192 offset:64
	ds_read_b128 v[222:225], v192 offset:96
	ds_read_b128 v[226:229], v192 offset:128
	ds_read_b128 v[230:233], v192 offset:160
	s_waitcnt lgkmcnt(5)
	v_mfma_f32_32x32x16_bf16 v[128:143], v[210:213], v[0:3], 0
	ds_read_b128 v[210:213], v192 offset:192
	s_waitcnt lgkmcnt(5)
	v_mfma_f32_32x32x16_bf16 v[128:143], v[214:217], v[4:7], v[128:143]
	ds_read_b128 v[214:217], v192 offset:224
	s_waitcnt lgkmcnt(5)
	v_mfma_f32_32x32x16_bf16 v[128:143], v[218:221], v[8:11], v[128:143]
	ds_read_b128 v[218:221], v192 offset:256
	s_waitcnt lgkmcnt(5)
	v_mfma_f32_32x32x16_bf16 v[128:143], v[222:225], v[12:15], v[128:143]
	ds_read_b128 v[222:225], v192 offset:288
	s_waitcnt lgkmcnt(5)
	v_mfma_f32_32x32x16_bf16 v[128:143], v[226:229], v[16:19], v[128:143]
	ds_read_b128 v[226:229], v192 offset:320
	s_waitcnt lgkmcnt(5)
	v_mfma_f32_32x32x16_bf16 v[128:143], v[230:233], v[20:23], v[128:143]
	ds_read_b128 v[230:233], v192 offset:352
	s_waitcnt lgkmcnt(5)
	v_mfma_f32_32x32x16_bf16 v[128:143], v[210:213], v[24:27], v[128:143]
	ds_read_b128 v[210:213], v192 offset:384
	s_waitcnt lgkmcnt(5)
	v_mfma_f32_32x32x16_bf16 v[128:143], v[214:217], v[28:31], v[128:143]
	ds_read_b128 v[214:217], v192 offset:416
	s_waitcnt lgkmcnt(5)
	v_mfma_f32_32x32x16_bf16 v[128:143], v[218:221], v[32:35], v[128:143]
	ds_read_b128 v[218:221], v192 offset:448
	s_waitcnt lgkmcnt(5)
	v_mfma_f32_32x32x16_bf16 v[128:143], v[222:225], v[36:39], v[128:143]
	ds_read_b128 v[222:225], v192 offset:480
	s_waitcnt lgkmcnt(5)
	v_mfma_f32_32x32x16_bf16 v[128:143], v[226:229], v[40:43], v[128:143]
	s_waitcnt lgkmcnt(4)
	v_mfma_f32_32x32x16_bf16 v[128:143], v[230:233], v[44:47], v[128:143]
	s_waitcnt lgkmcnt(3)
	v_mfma_f32_32x32x16_bf16 v[128:143], v[210:213], v[48:51], v[128:143]
	s_waitcnt lgkmcnt(2)
	v_mfma_f32_32x32x16_bf16 v[128:143], v[214:217], v[52:55], v[128:143]
	s_waitcnt lgkmcnt(1)
	v_mfma_f32_32x32x16_bf16 v[128:143], v[218:221], v[56:59], v[128:143]
	s_waitcnt lgkmcnt(0)
	v_mfma_f32_32x32x16_bf16 v[128:143], v[222:225], v[60:63], v[128:143]
	s_waitcnt vmcnt(2)
	s_barrier
	ds_write_b128 v193, v[242:245]
	ds_write_b128 v193, v[246:249] offset:8448
	s_add_u32 s70, s54, 0x70000
	s_addc_u32 s71, s55, 0
	s_add_u32 s72, s54, 0x78000
	s_addc_u32 s73, s55, 0
	global_load_dwordx4 v[242:245], v194, s[70:71]
	global_load_dwordx4 v[246:249], v194, s[72:73]
	s_waitcnt lgkmcnt(0)
	s_barrier
	ds_read_b128 v[210:213], v192
	ds_read_b128 v[214:217], v192 offset:32
	ds_read_b128 v[218:221], v192 offset:64
	ds_read_b128 v[222:225], v192 offset:96
	ds_read_b128 v[226:229], v192 offset:128
	ds_read_b128 v[230:233], v192 offset:160
	s_waitcnt lgkmcnt(5)
	v_mfma_f32_32x32x16_bf16 v[144:159], v[210:213], v[0:3], 0
	ds_read_b128 v[210:213], v192 offset:192
	s_waitcnt lgkmcnt(5)
	v_mfma_f32_32x32x16_bf16 v[144:159], v[214:217], v[4:7], v[144:159]
	ds_read_b128 v[214:217], v192 offset:224
	s_waitcnt lgkmcnt(5)
	v_mfma_f32_32x32x16_bf16 v[144:159], v[218:221], v[8:11], v[144:159]
	ds_read_b128 v[218:221], v192 offset:256
	s_waitcnt lgkmcnt(5)
	v_mfma_f32_32x32x16_bf16 v[144:159], v[222:225], v[12:15], v[144:159]
	ds_read_b128 v[222:225], v192 offset:288
	s_waitcnt lgkmcnt(5)
	v_mfma_f32_32x32x16_bf16 v[144:159], v[226:229], v[16:19], v[144:159]
	ds_read_b128 v[226:229], v192 offset:320
	s_waitcnt lgkmcnt(5)
	v_mfma_f32_32x32x16_bf16 v[144:159], v[230:233], v[20:23], v[144:159]
	ds_read_b128 v[230:233], v192 offset:352
	s_waitcnt lgkmcnt(5)
	v_mfma_f32_32x32x16_bf16 v[144:159], v[210:213], v[24:27], v[144:159]
	ds_read_b128 v[210:213], v192 offset:384
	s_waitcnt lgkmcnt(5)
	v_mfma_f32_32x32x16_bf16 v[144:159], v[214:217], v[28:31], v[144:159]
	ds_read_b128 v[214:217], v192 offset:416
	s_waitcnt lgkmcnt(5)
	v_mfma_f32_32x32x16_bf16 v[144:159], v[218:221], v[32:35], v[144:159]
	ds_read_b128 v[218:221], v192 offset:448
	s_waitcnt lgkmcnt(5)
	v_mfma_f32_32x32x16_bf16 v[144:159], v[222:225], v[36:39], v[144:159]
	ds_read_b128 v[222:225], v192 offset:480
	s_waitcnt lgkmcnt(5)
	v_mfma_f32_32x32x16_bf16 v[144:159], v[226:229], v[40:43], v[144:159]
	s_waitcnt lgkmcnt(4)
	v_mfma_f32_32x32x16_bf16 v[144:159], v[230:233], v[44:47], v[144:159]
	s_waitcnt lgkmcnt(3)
	v_mfma_f32_32x32x16_bf16 v[144:159], v[210:213], v[48:51], v[144:159]
	s_waitcnt lgkmcnt(2)
	v_mfma_f32_32x32x16_bf16 v[144:159], v[214:217], v[52:55], v[144:159]
	s_waitcnt lgkmcnt(1)
	v_mfma_f32_32x32x16_bf16 v[144:159], v[218:221], v[56:59], v[144:159]
	s_waitcnt lgkmcnt(0)
	v_mfma_f32_32x32x16_bf16 v[144:159], v[222:225], v[60:63], v[144:159]
	s_waitcnt vmcnt(2)
	s_barrier
	ds_write_b128 v193, v[234:237]
	ds_write_b128 v193, v[238:241] offset:8448
	s_add_u32 s70, s54, 0
	s_addc_u32 s71, s55, 0
	s_add_u32 s72, s54, 0x8000
	s_addc_u32 s73, s55, 0
	global_load_dwordx4 v[234:237], v194, s[70:71]
	global_load_dwordx4 v[238:241], v194, s[72:73]
	s_waitcnt lgkmcnt(0)
	s_barrier
	ds_read_b128 v[210:213], v192
	ds_read_b128 v[214:217], v192 offset:32
	ds_read_b128 v[218:221], v192 offset:64
	ds_read_b128 v[222:225], v192 offset:96
	ds_read_b128 v[226:229], v192 offset:128
	ds_read_b128 v[230:233], v192 offset:160
	s_waitcnt lgkmcnt(5)
	v_mfma_f32_32x32x16_bf16 v[160:175], v[210:213], v[0:3], 0
	ds_read_b128 v[210:213], v192 offset:192
	s_waitcnt lgkmcnt(5)
	v_mfma_f32_32x32x16_bf16 v[160:175], v[214:217], v[4:7], v[160:175]
	ds_read_b128 v[214:217], v192 offset:224
	s_waitcnt lgkmcnt(5)
	v_mfma_f32_32x32x16_bf16 v[160:175], v[218:221], v[8:11], v[160:175]
	ds_read_b128 v[218:221], v192 offset:256
	s_waitcnt lgkmcnt(5)
	v_mfma_f32_32x32x16_bf16 v[160:175], v[222:225], v[12:15], v[160:175]
	ds_read_b128 v[222:225], v192 offset:288
	s_waitcnt lgkmcnt(5)
	v_mfma_f32_32x32x16_bf16 v[160:175], v[226:229], v[16:19], v[160:175]
	ds_read_b128 v[226:229], v192 offset:320
	s_waitcnt lgkmcnt(5)
	v_mfma_f32_32x32x16_bf16 v[160:175], v[230:233], v[20:23], v[160:175]
	ds_read_b128 v[230:233], v192 offset:352
	s_waitcnt lgkmcnt(5)
	v_mfma_f32_32x32x16_bf16 v[160:175], v[210:213], v[24:27], v[160:175]
	ds_read_b128 v[210:213], v192 offset:384
	s_waitcnt lgkmcnt(5)
	v_mfma_f32_32x32x16_bf16 v[160:175], v[214:217], v[28:31], v[160:175]
	ds_read_b128 v[214:217], v192 offset:416
	s_waitcnt lgkmcnt(5)
	v_mfma_f32_32x32x16_bf16 v[160:175], v[218:221], v[32:35], v[160:175]
	ds_read_b128 v[218:221], v192 offset:448
	s_waitcnt lgkmcnt(5)
	v_mfma_f32_32x32x16_bf16 v[160:175], v[222:225], v[36:39], v[160:175]
	ds_read_b128 v[222:225], v192 offset:480
	s_waitcnt lgkmcnt(5)
	v_mfma_f32_32x32x16_bf16 v[160:175], v[226:229], v[40:43], v[160:175]
	s_waitcnt lgkmcnt(4)
	v_mfma_f32_32x32x16_bf16 v[160:175], v[230:233], v[44:47], v[160:175]
	s_waitcnt lgkmcnt(3)
	v_mfma_f32_32x32x16_bf16 v[160:175], v[210:213], v[48:51], v[160:175]
	s_waitcnt lgkmcnt(2)
	v_mfma_f32_32x32x16_bf16 v[160:175], v[214:217], v[52:55], v[160:175]
	s_waitcnt lgkmcnt(1)
	v_mfma_f32_32x32x16_bf16 v[160:175], v[218:221], v[56:59], v[160:175]
	s_waitcnt lgkmcnt(0)
	v_mfma_f32_32x32x16_bf16 v[160:175], v[222:225], v[60:63], v[160:175]
	s_waitcnt vmcnt(2)
	s_barrier
	ds_write_b128 v193, v[242:245]
	ds_write_b128 v193, v[246:249] offset:8448
	s_add_u32 s70, s54, 0x10000
	s_addc_u32 s71, s55, 0
	s_add_u32 s72, s54, 0x18000
	s_addc_u32 s73, s55, 0
	global_load_dwordx4 v[242:245], v194, s[70:71]
	global_load_dwordx4 v[246:249], v194, s[72:73]
	s_waitcnt lgkmcnt(0)
	s_barrier
	ds_read_b128 v[210:213], v192
	ds_read_b128 v[214:217], v192 offset:32
	ds_read_b128 v[218:221], v192 offset:64
	ds_read_b128 v[222:225], v192 offset:96
	ds_read_b128 v[226:229], v192 offset:128
	ds_read_b128 v[230:233], v192 offset:160
	s_waitcnt lgkmcnt(5)
	v_mfma_f32_32x32x16_bf16 v[176:191], v[210:213], v[0:3], 0
	ds_read_b128 v[210:213], v192 offset:192
	s_waitcnt lgkmcnt(5)
	v_mfma_f32_32x32x16_bf16 v[176:191], v[214:217], v[4:7], v[176:191]
	ds_read_b128 v[214:217], v192 offset:224
	s_waitcnt lgkmcnt(5)
	v_mfma_f32_32x32x16_bf16 v[176:191], v[218:221], v[8:11], v[176:191]
	ds_read_b128 v[218:221], v192 offset:256
	s_waitcnt lgkmcnt(5)
	v_mfma_f32_32x32x16_bf16 v[176:191], v[222:225], v[12:15], v[176:191]
	ds_read_b128 v[222:225], v192 offset:288
	s_waitcnt lgkmcnt(5)
	v_mfma_f32_32x32x16_bf16 v[176:191], v[226:229], v[16:19], v[176:191]
	ds_read_b128 v[226:229], v192 offset:320
	s_waitcnt lgkmcnt(5)
	v_mfma_f32_32x32x16_bf16 v[176:191], v[230:233], v[20:23], v[176:191]
	ds_read_b128 v[230:233], v192 offset:352
	s_waitcnt lgkmcnt(5)
	v_mfma_f32_32x32x16_bf16 v[176:191], v[210:213], v[24:27], v[176:191]
	ds_read_b128 v[210:213], v192 offset:384
	s_waitcnt lgkmcnt(5)
	v_mfma_f32_32x32x16_bf16 v[176:191], v[214:217], v[28:31], v[176:191]
	ds_read_b128 v[214:217], v192 offset:416
	s_waitcnt lgkmcnt(5)
	v_mfma_f32_32x32x16_bf16 v[176:191], v[218:221], v[32:35], v[176:191]
	ds_read_b128 v[218:221], v192 offset:448
	s_waitcnt lgkmcnt(5)
	v_mfma_f32_32x32x16_bf16 v[176:191], v[222:225], v[36:39], v[176:191]
	ds_read_b128 v[222:225], v192 offset:480
	s_waitcnt lgkmcnt(5)
	v_mfma_f32_32x32x16_bf16 v[176:191], v[226:229], v[40:43], v[176:191]
	s_waitcnt lgkmcnt(4)
	v_mfma_f32_32x32x16_bf16 v[176:191], v[230:233], v[44:47], v[176:191]
	s_waitcnt lgkmcnt(3)
	v_mfma_f32_32x32x16_bf16 v[176:191], v[210:213], v[48:51], v[176:191]
	s_waitcnt lgkmcnt(2)
	v_mfma_f32_32x32x16_bf16 v[176:191], v[214:217], v[52:55], v[176:191]
	s_waitcnt lgkmcnt(1)
	v_mfma_f32_32x32x16_bf16 v[176:191], v[218:221], v[56:59], v[176:191]
	s_waitcnt lgkmcnt(0)
	v_mfma_f32_32x32x16_bf16 v[176:191], v[222:225], v[60:63], v[176:191]
	s_nop 7
	s_nop 3
	v_max3_f32 v198, v64, v65, v66
	v_max3_f32 v198, v67, v68, v198
	v_max3_f32 v198, v69, v70, v198
	v_max3_f32 v198, v71, v72, v198
	v_max3_f32 v198, v73, v74, v198
	v_max3_f32 v198, v75, v76, v198
	v_max3_f32 v198, v77, v78, v198
	v_max3_f32 v198, v79, v80, v198
	v_max3_f32 v198, v81, v82, v198
	v_max3_f32 v198, v83, v84, v198
	v_max3_f32 v198, v85, v86, v198
	v_max3_f32 v198, v87, v88, v198
	v_max3_f32 v198, v89, v90, v198
	v_max3_f32 v198, v91, v92, v198
	v_max3_f32 v198, v93, v94, v198
	v_max3_f32 v198, v95, v96, v198
	v_max3_f32 v198, v97, v98, v198
	v_max3_f32 v198, v99, v100, v198
	v_max3_f32 v198, v101, v102, v198
	v_max3_f32 v198, v103, v104, v198
	v_max3_f32 v198, v105, v106, v198
	v_max3_f32 v198, v107, v108, v198
	v_max3_f32 v198, v109, v110, v198
	v_max3_f32 v198, v111, v112, v198
	v_max3_f32 v198, v113, v114, v198
	v_max3_f32 v198, v115, v116, v198
	v_max3_f32 v198, v117, v118, v198
	v_max3_f32 v198, v119, v120, v198
	v_max3_f32 v198, v121, v122, v198
	v_max3_f32 v198, v123, v124, v198
	v_max3_f32 v198, v125, v126, v198
	v_max3_f32 v198, v127, v128, v198
	v_max3_f32 v198, v129, v130, v198
	v_max3_f32 v198, v131, v132, v198
	v_max3_f32 v198, v133, v134, v198
	v_max3_f32 v198, v135, v136, v198
	v_max3_f32 v198, v137, v138, v198
	v_max3_f32 v198, v139, v140, v198
	v_max3_f32 v198, v141, v142, v198
	v_max3_f32 v198, v143, v144, v198
	v_max3_f32 v198, v145, v146, v198
	v_max3_f32 v198, v147, v148, v198
	v_max3_f32 v198, v149, v150, v198
	v_max3_f32 v198, v151, v152, v198
	v_max3_f32 v198, v153, v154, v198
	v_max3_f32 v198, v155, v156, v198
	v_max3_f32 v198, v157, v158, v198
	v_max3_f32 v198, v159, v160, v198
	v_max3_f32 v198, v161, v162, v198
	v_max3_f32 v198, v163, v164, v198
	v_max3_f32 v198, v165, v166, v198
	v_max3_f32 v198, v167, v168, v198
	v_max3_f32 v198, v169, v170, v198
	v_max3_f32 v198, v171, v172, v198
	v_max3_f32 v198, v173, v174, v198
	v_max3_f32 v198, v175, v176, v198
	v_max3_f32 v198, v177, v178, v198
	v_max3_f32 v198, v179, v180, v198
	v_max3_f32 v198, v181, v182, v198
	v_max3_f32 v198, v183, v184, v198
	v_max3_f32 v198, v185, v186, v198
	v_max3_f32 v198, v187, v188, v198
	v_max3_f32 v198, v189, v190, v198
	v_max_f32_e32 v198, v191, v198
	v_mov_b32_e32 v200, v198
	v_mov_b32_e32 v201, v198
	s_nop 1
	v_permlane32_swap_b32_e32 v200, v201
	v_max3_f32 v198, v198, v200, v201
	v_sub_f32_e32 v64, v64, v198
	v_sub_f32_e32 v65, v65, v198
	v_sub_f32_e32 v66, v66, v198
	v_sub_f32_e32 v67, v67, v198
	v_sub_f32_e32 v68, v68, v198
	v_sub_f32_e32 v69, v69, v198
	v_sub_f32_e32 v70, v70, v198
	v_sub_f32_e32 v71, v71, v198
	v_exp_f32_e32 v64, v64
	v_exp_f32_e32 v65, v65
	v_exp_f32_e32 v66, v66
	v_exp_f32_e32 v67, v67
	v_exp_f32_e32 v68, v68
	v_exp_f32_e32 v69, v69
	v_exp_f32_e32 v70, v70
	v_exp_f32_e32 v71, v71
	v_sub_f32_e32 v72, v72, v198
	v_sub_f32_e32 v73, v73, v198
	v_sub_f32_e32 v74, v74, v198
	v_sub_f32_e32 v75, v75, v198
	v_sub_f32_e32 v76, v76, v198
	v_sub_f32_e32 v77, v77, v198
	v_sub_f32_e32 v78, v78, v198
	v_sub_f32_e32 v79, v79, v198
	v_exp_f32_e32 v72, v72
	v_exp_f32_e32 v73, v73
	v_exp_f32_e32 v74, v74
	v_exp_f32_e32 v75, v75
	v_exp_f32_e32 v76, v76
	v_exp_f32_e32 v77, v77
	v_exp_f32_e32 v78, v78
	v_exp_f32_e32 v79, v79
	v_sub_f32_e32 v80, v80, v198
	v_sub_f32_e32 v81, v81, v198
	v_sub_f32_e32 v82, v82, v198
	v_sub_f32_e32 v83, v83, v198
	v_sub_f32_e32 v84, v84, v198
	v_sub_f32_e32 v85, v85, v198
	v_sub_f32_e32 v86, v86, v198
	v_sub_f32_e32 v87, v87, v198
	v_exp_f32_e32 v80, v80
	v_exp_f32_e32 v81, v81
	v_exp_f32_e32 v82, v82
	v_exp_f32_e32 v83, v83
	v_exp_f32_e32 v84, v84
	v_exp_f32_e32 v85, v85
	v_exp_f32_e32 v86, v86
	v_exp_f32_e32 v87, v87
	v_sub_f32_e32 v88, v88, v198
	v_sub_f32_e32 v89, v89, v198
	v_sub_f32_e32 v90, v90, v198
	v_sub_f32_e32 v91, v91, v198
	v_sub_f32_e32 v92, v92, v198
	v_sub_f32_e32 v93, v93, v198
	v_sub_f32_e32 v94, v94, v198
	v_sub_f32_e32 v95, v95, v198
	v_exp_f32_e32 v88, v88
	v_exp_f32_e32 v89, v89
	v_exp_f32_e32 v90, v90
	v_exp_f32_e32 v91, v91
	v_exp_f32_e32 v92, v92
	v_exp_f32_e32 v93, v93
	v_exp_f32_e32 v94, v94
	v_exp_f32_e32 v95, v95
	v_sub_f32_e32 v96, v96, v198
	v_sub_f32_e32 v97, v97, v198
	v_sub_f32_e32 v98, v98, v198
	v_sub_f32_e32 v99, v99, v198
	v_sub_f32_e32 v100, v100, v198
	v_sub_f32_e32 v101, v101, v198
	v_sub_f32_e32 v102, v102, v198
	v_sub_f32_e32 v103, v103, v198
	v_exp_f32_e32 v96, v96
	v_exp_f32_e32 v97, v97
	v_exp_f32_e32 v98, v98
	v_exp_f32_e32 v99, v99
	v_exp_f32_e32 v100, v100
	v_exp_f32_e32 v101, v101
	v_exp_f32_e32 v102, v102
	v_exp_f32_e32 v103, v103
	v_sub_f32_e32 v104, v104, v198
	v_sub_f32_e32 v105, v105, v198
	v_sub_f32_e32 v106, v106, v198
	v_sub_f32_e32 v107, v107, v198
	v_sub_f32_e32 v108, v108, v198
	v_sub_f32_e32 v109, v109, v198
	v_sub_f32_e32 v110, v110, v198
	v_sub_f32_e32 v111, v111, v198
	v_exp_f32_e32 v104, v104
	v_exp_f32_e32 v105, v105
	v_exp_f32_e32 v106, v106
	v_exp_f32_e32 v107, v107
	v_exp_f32_e32 v108, v108
	v_exp_f32_e32 v109, v109
	v_exp_f32_e32 v110, v110
	v_exp_f32_e32 v111, v111
	v_sub_f32_e32 v112, v112, v198
	v_sub_f32_e32 v113, v113, v198
	v_sub_f32_e32 v114, v114, v198
	v_sub_f32_e32 v115, v115, v198
	v_sub_f32_e32 v116, v116, v198
	v_sub_f32_e32 v117, v117, v198
	v_sub_f32_e32 v118, v118, v198
	v_sub_f32_e32 v119, v119, v198
	v_exp_f32_e32 v112, v112
	v_exp_f32_e32 v113, v113
	v_exp_f32_e32 v114, v114
	v_exp_f32_e32 v115, v115
	v_exp_f32_e32 v116, v116
	v_exp_f32_e32 v117, v117
	v_exp_f32_e32 v118, v118
	v_exp_f32_e32 v119, v119
	v_sub_f32_e32 v120, v120, v198
	v_sub_f32_e32 v121, v121, v198
	v_sub_f32_e32 v122, v122, v198
	v_sub_f32_e32 v123, v123, v198
	v_sub_f32_e32 v124, v124, v198
	v_sub_f32_e32 v125, v125, v198
	v_sub_f32_e32 v126, v126, v198
	v_sub_f32_e32 v127, v127, v198
	v_exp_f32_e32 v120, v120
	v_exp_f32_e32 v121, v121
	v_exp_f32_e32 v122, v122
	v_exp_f32_e32 v123, v123
	v_exp_f32_e32 v124, v124
	v_exp_f32_e32 v125, v125
	v_exp_f32_e32 v126, v126
	v_exp_f32_e32 v127, v127
	v_sub_f32_e32 v128, v128, v198
	v_sub_f32_e32 v129, v129, v198
	v_sub_f32_e32 v130, v130, v198
	v_sub_f32_e32 v131, v131, v198
	v_sub_f32_e32 v132, v132, v198
	v_sub_f32_e32 v133, v133, v198
	v_sub_f32_e32 v134, v134, v198
	v_sub_f32_e32 v135, v135, v198
	v_exp_f32_e32 v128, v128
	v_exp_f32_e32 v129, v129
	v_exp_f32_e32 v130, v130
	v_exp_f32_e32 v131, v131
	v_exp_f32_e32 v132, v132
	v_exp_f32_e32 v133, v133
	v_exp_f32_e32 v134, v134
	v_exp_f32_e32 v135, v135
	v_sub_f32_e32 v136, v136, v198
	v_sub_f32_e32 v137, v137, v198
	v_sub_f32_e32 v138, v138, v198
	v_sub_f32_e32 v139, v139, v198
	v_sub_f32_e32 v140, v140, v198
	v_sub_f32_e32 v141, v141, v198
	v_sub_f32_e32 v142, v142, v198
	v_sub_f32_e32 v143, v143, v198
	v_exp_f32_e32 v136, v136
	v_exp_f32_e32 v137, v137
	v_exp_f32_e32 v138, v138
	v_exp_f32_e32 v139, v139
	v_exp_f32_e32 v140, v140
	v_exp_f32_e32 v141, v141
	v_exp_f32_e32 v142, v142
	v_exp_f32_e32 v143, v143
	v_sub_f32_e32 v144, v144, v198
	v_sub_f32_e32 v145, v145, v198
	v_sub_f32_e32 v146, v146, v198
	v_sub_f32_e32 v147, v147, v198
	v_sub_f32_e32 v148, v148, v198
	v_sub_f32_e32 v149, v149, v198
	v_sub_f32_e32 v150, v150, v198
	v_sub_f32_e32 v151, v151, v198
	v_exp_f32_e32 v144, v144
	v_exp_f32_e32 v145, v145
	v_exp_f32_e32 v146, v146
	v_exp_f32_e32 v147, v147
	v_exp_f32_e32 v148, v148
	v_exp_f32_e32 v149, v149
	v_exp_f32_e32 v150, v150
	v_exp_f32_e32 v151, v151
	v_sub_f32_e32 v152, v152, v198
	v_sub_f32_e32 v153, v153, v198
	v_sub_f32_e32 v154, v154, v198
	v_sub_f32_e32 v155, v155, v198
	v_sub_f32_e32 v156, v156, v198
	v_sub_f32_e32 v157, v157, v198
	v_sub_f32_e32 v158, v158, v198
	v_sub_f32_e32 v159, v159, v198
	v_exp_f32_e32 v152, v152
	v_exp_f32_e32 v153, v153
	v_exp_f32_e32 v154, v154
	v_exp_f32_e32 v155, v155
	v_exp_f32_e32 v156, v156
	v_exp_f32_e32 v157, v157
	v_exp_f32_e32 v158, v158
	v_exp_f32_e32 v159, v159
	v_sub_f32_e32 v160, v160, v198
	v_sub_f32_e32 v161, v161, v198
	v_sub_f32_e32 v162, v162, v198
	v_sub_f32_e32 v163, v163, v198
	v_sub_f32_e32 v164, v164, v198
	v_sub_f32_e32 v165, v165, v198
	v_sub_f32_e32 v166, v166, v198
	v_sub_f32_e32 v167, v167, v198
	v_exp_f32_e32 v160, v160
	v_exp_f32_e32 v161, v161
	v_exp_f32_e32 v162, v162
	v_exp_f32_e32 v163, v163
	v_exp_f32_e32 v164, v164
	v_exp_f32_e32 v165, v165
	v_exp_f32_e32 v166, v166
	v_exp_f32_e32 v167, v167
	v_sub_f32_e32 v168, v168, v198
	v_sub_f32_e32 v169, v169, v198
	v_sub_f32_e32 v170, v170, v198
	v_sub_f32_e32 v171, v171, v198
	v_sub_f32_e32 v172, v172, v198
	v_sub_f32_e32 v173, v173, v198
	v_sub_f32_e32 v174, v174, v198
	v_sub_f32_e32 v175, v175, v198
	v_exp_f32_e32 v168, v168
	v_exp_f32_e32 v169, v169
	v_exp_f32_e32 v170, v170
	v_exp_f32_e32 v171, v171
	v_exp_f32_e32 v172, v172
	v_exp_f32_e32 v173, v173
	v_exp_f32_e32 v174, v174
	v_exp_f32_e32 v175, v175
	v_sub_f32_e32 v176, v176, v198
	v_sub_f32_e32 v177, v177, v198
	v_sub_f32_e32 v178, v178, v198
	v_sub_f32_e32 v179, v179, v198
	v_sub_f32_e32 v180, v180, v198
	v_sub_f32_e32 v181, v181, v198
	v_sub_f32_e32 v182, v182, v198
	v_sub_f32_e32 v183, v183, v198
	v_exp_f32_e32 v176, v176
	v_exp_f32_e32 v177, v177
	v_exp_f32_e32 v178, v178
	v_exp_f32_e32 v179, v179
	v_exp_f32_e32 v180, v180
	v_exp_f32_e32 v181, v181
	v_exp_f32_e32 v182, v182
	v_exp_f32_e32 v183, v183
	v_sub_f32_e32 v184, v184, v198
	v_sub_f32_e32 v185, v185, v198
	v_sub_f32_e32 v186, v186, v198
	v_sub_f32_e32 v187, v187, v198
	v_sub_f32_e32 v188, v188, v198
	v_sub_f32_e32 v189, v189, v198
	v_sub_f32_e32 v190, v190, v198
	v_sub_f32_e32 v191, v191, v198
	v_exp_f32_e32 v184, v184
	v_exp_f32_e32 v185, v185
	v_exp_f32_e32 v186, v186
	v_exp_f32_e32 v187, v187
	v_exp_f32_e32 v188, v188
	v_exp_f32_e32 v189, v189
	v_exp_f32_e32 v190, v190
	v_exp_f32_e32 v191, v191
	s_nop 0
	v_add_f32_e32 v199, v64, v65
	v_add_f32_e32 v205, v66, v67
	v_add_f32_e32 v199, v199, v68
	v_add_f32_e32 v205, v205, v69
	v_add_f32_e32 v199, v199, v70
	v_add_f32_e32 v205, v205, v71
	v_add_f32_e32 v199, v199, v72
	v_add_f32_e32 v205, v205, v73
	v_add_f32_e32 v199, v199, v74
	v_add_f32_e32 v205, v205, v75
	v_add_f32_e32 v199, v199, v76
	v_add_f32_e32 v205, v205, v77
	v_add_f32_e32 v199, v199, v78
	v_add_f32_e32 v205, v205, v79
	v_add_f32_e32 v199, v199, v80
	v_add_f32_e32 v205, v205, v81
	v_add_f32_e32 v199, v199, v82
	v_add_f32_e32 v205, v205, v83
	v_add_f32_e32 v199, v199, v84
	v_add_f32_e32 v205, v205, v85
	v_add_f32_e32 v199, v199, v86
	v_add_f32_e32 v205, v205, v87
	v_add_f32_e32 v199, v199, v88
	v_add_f32_e32 v205, v205, v89
	v_add_f32_e32 v199, v199, v90
	v_add_f32_e32 v205, v205, v91
	v_add_f32_e32 v199, v199, v92
	v_add_f32_e32 v205, v205, v93
	v_add_f32_e32 v199, v199, v94
	v_add_f32_e32 v205, v205, v95
	v_add_f32_e32 v199, v199, v96
	v_add_f32_e32 v205, v205, v97
	v_add_f32_e32 v199, v199, v98
	v_add_f32_e32 v205, v205, v99
	v_add_f32_e32 v199, v199, v100
	v_add_f32_e32 v205, v205, v101
	v_add_f32_e32 v199, v199, v102
	v_add_f32_e32 v205, v205, v103
	v_add_f32_e32 v199, v199, v104
	v_add_f32_e32 v205, v205, v105
	v_add_f32_e32 v199, v199, v106
	v_add_f32_e32 v205, v205, v107
	v_add_f32_e32 v199, v199, v108
	v_add_f32_e32 v205, v205, v109
	v_add_f32_e32 v199, v199, v110
	v_add_f32_e32 v205, v205, v111
	v_add_f32_e32 v199, v199, v112
	v_add_f32_e32 v205, v205, v113
	v_add_f32_e32 v199, v199, v114
	v_add_f32_e32 v205, v205, v115
	v_add_f32_e32 v199, v199, v116
	v_add_f32_e32 v205, v205, v117
	v_add_f32_e32 v199, v199, v118
	v_add_f32_e32 v205, v205, v119
	v_add_f32_e32 v199, v199, v120
	v_add_f32_e32 v205, v205, v121
	v_add_f32_e32 v199, v199, v122
	v_add_f32_e32 v205, v205, v123
	v_add_f32_e32 v199, v199, v124
	v_add_f32_e32 v205, v205, v125
	v_add_f32_e32 v199, v199, v126
	v_add_f32_e32 v205, v205, v127
	v_add_f32_e32 v199, v199, v128
	v_add_f32_e32 v205, v205, v129
	v_add_f32_e32 v199, v199, v130
	v_add_f32_e32 v205, v205, v131
	v_add_f32_e32 v199, v199, v132
	v_add_f32_e32 v205, v205, v133
	v_add_f32_e32 v199, v199, v134
	v_add_f32_e32 v205, v205, v135
	v_add_f32_e32 v199, v199, v136
	v_add_f32_e32 v205, v205, v137
	v_add_f32_e32 v199, v199, v138
	v_add_f32_e32 v205, v205, v139
	v_add_f32_e32 v199, v199, v140
	v_add_f32_e32 v205, v205, v141
	v_add_f32_e32 v199, v199, v142
	v_add_f32_e32 v205, v205, v143
	v_add_f32_e32 v199, v199, v144
	v_add_f32_e32 v205, v205, v145
	v_add_f32_e32 v199, v199, v146
	v_add_f32_e32 v205, v205, v147
	v_add_f32_e32 v199, v199, v148
	v_add_f32_e32 v205, v205, v149
	v_add_f32_e32 v199, v199, v150
	v_add_f32_e32 v205, v205, v151
	v_add_f32_e32 v199, v199, v152
	v_add_f32_e32 v205, v205, v153
	v_add_f32_e32 v199, v199, v154
	v_add_f32_e32 v205, v205, v155
	v_add_f32_e32 v199, v199, v156
	v_add_f32_e32 v205, v205, v157
	v_add_f32_e32 v199, v199, v158
	v_add_f32_e32 v205, v205, v159
	v_add_f32_e32 v199, v199, v160
	v_add_f32_e32 v205, v205, v161
	v_add_f32_e32 v199, v199, v162
	v_add_f32_e32 v205, v205, v163
	v_add_f32_e32 v199, v199, v164
	v_add_f32_e32 v205, v205, v165
	v_add_f32_e32 v199, v199, v166
	v_add_f32_e32 v205, v205, v167
	v_add_f32_e32 v199, v199, v168
	v_add_f32_e32 v205, v205, v169
	v_add_f32_e32 v199, v199, v170
	v_add_f32_e32 v205, v205, v171
	v_add_f32_e32 v199, v199, v172
	v_add_f32_e32 v205, v205, v173
	v_add_f32_e32 v199, v199, v174
	v_add_f32_e32 v205, v205, v175
	v_add_f32_e32 v199, v199, v176
	v_add_f32_e32 v205, v205, v177
	v_add_f32_e32 v199, v199, v178
	v_add_f32_e32 v205, v205, v179
	v_add_f32_e32 v199, v199, v180
	v_add_f32_e32 v205, v205, v181
	v_add_f32_e32 v199, v199, v182
	v_add_f32_e32 v205, v205, v183
	v_add_f32_e32 v199, v199, v184
	v_add_f32_e32 v205, v205, v185
	v_add_f32_e32 v199, v199, v186
	v_add_f32_e32 v205, v205, v187
	v_add_f32_e32 v199, v199, v188
	v_add_f32_e32 v205, v205, v189
	v_add_f32_e32 v199, v199, v190
	v_add_f32_e32 v205, v205, v191
	v_cvt_pk_bf16_f32 v0, v64, v65
	v_cvt_pk_bf16_f32 v1, v66, v67
	v_cvt_pk_bf16_f32 v2, v68, v69
	v_cvt_pk_bf16_f32 v3, v70, v71
	v_cvt_pk_bf16_f32 v4, v72, v73
	v_cvt_pk_bf16_f32 v5, v74, v75
	v_cvt_pk_bf16_f32 v6, v76, v77
	v_cvt_pk_bf16_f32 v7, v78, v79
	v_cvt_pk_bf16_f32 v8, v80, v81
	v_cvt_pk_bf16_f32 v9, v82, v83
	v_cvt_pk_bf16_f32 v10, v84, v85
	v_cvt_pk_bf16_f32 v11, v86, v87
	v_cvt_pk_bf16_f32 v12, v88, v89
	v_cvt_pk_bf16_f32 v13, v90, v91
	v_cvt_pk_bf16_f32 v14, v92, v93
	v_cvt_pk_bf16_f32 v15, v94, v95
	v_cvt_pk_bf16_f32 v16, v96, v97
	v_cvt_pk_bf16_f32 v17, v98, v99
	v_cvt_pk_bf16_f32 v18, v100, v101
	v_cvt_pk_bf16_f32 v19, v102, v103
	v_cvt_pk_bf16_f32 v20, v104, v105
	v_cvt_pk_bf16_f32 v21, v106, v107
	v_cvt_pk_bf16_f32 v22, v108, v109
	v_cvt_pk_bf16_f32 v23, v110, v111
	v_cvt_pk_bf16_f32 v24, v112, v113
	v_cvt_pk_bf16_f32 v25, v114, v115
	v_cvt_pk_bf16_f32 v26, v116, v117
	v_cvt_pk_bf16_f32 v27, v118, v119
	v_cvt_pk_bf16_f32 v28, v120, v121
	v_cvt_pk_bf16_f32 v29, v122, v123
	v_cvt_pk_bf16_f32 v30, v124, v125
	v_cvt_pk_bf16_f32 v31, v126, v127
	v_cvt_pk_bf16_f32 v32, v128, v129
	v_cvt_pk_bf16_f32 v33, v130, v131
	v_cvt_pk_bf16_f32 v34, v132, v133
	v_cvt_pk_bf16_f32 v35, v134, v135
	v_cvt_pk_bf16_f32 v36, v136, v137
	v_cvt_pk_bf16_f32 v37, v138, v139
	v_cvt_pk_bf16_f32 v38, v140, v141
	v_cvt_pk_bf16_f32 v39, v142, v143
	v_cvt_pk_bf16_f32 v40, v144, v145
	v_cvt_pk_bf16_f32 v41, v146, v147
	v_cvt_pk_bf16_f32 v42, v148, v149
	v_cvt_pk_bf16_f32 v43, v150, v151
	v_cvt_pk_bf16_f32 v44, v152, v153
	v_cvt_pk_bf16_f32 v45, v154, v155
	v_cvt_pk_bf16_f32 v46, v156, v157
	v_cvt_pk_bf16_f32 v47, v158, v159
	v_cvt_pk_bf16_f32 v48, v160, v161
	v_cvt_pk_bf16_f32 v49, v162, v163
	v_cvt_pk_bf16_f32 v50, v164, v165
	v_cvt_pk_bf16_f32 v51, v166, v167
	v_cvt_pk_bf16_f32 v52, v168, v169
	v_cvt_pk_bf16_f32 v53, v170, v171
	v_cvt_pk_bf16_f32 v54, v172, v173
	v_cvt_pk_bf16_f32 v55, v174, v175
	v_cvt_pk_bf16_f32 v56, v176, v177
	v_cvt_pk_bf16_f32 v57, v178, v179
	v_cvt_pk_bf16_f32 v58, v180, v181
	v_cvt_pk_bf16_f32 v59, v182, v183
	v_cvt_pk_bf16_f32 v60, v184, v185
	v_cvt_pk_bf16_f32 v61, v186, v187
	v_cvt_pk_bf16_f32 v62, v188, v189
	v_cvt_pk_bf16_f32 v63, v190, v191
	v_add_f32_e32 v199, v199, v205
	v_mov_b32_e32 v200, v199
	v_mov_b32_e32 v201, v199
	s_nop 1
	v_permlane32_swap_b32_e32 v200, v201
	v_add_f32_e32 v200, v200, v201
	v_rcp_f32_e32 v199, v200
	ds_read_b128 v[210:213], v196
	ds_read_b128 v[214:217], v196 offset:16896
	ds_read_b128 v[218:221], v196 offset:33792
	ds_read_b128 v[222:225], v196 offset:50688
	ds_read_b128 v[226:229], v197
	ds_read_b128 v[230:233], v197 offset:16896
	s_waitcnt lgkmcnt(5)
	v_mfma_f32_32x32x16_bf16 v[64:79], v[210:213], v[0:3], 0
	ds_read_b128 v[210:213], v197 offset:33792
	s_waitcnt lgkmcnt(5)
	v_mfma_f32_32x32x16_bf16 v[80:95], v[214:217], v[0:3], 0
	ds_read_b128 v[214:217], v197 offset:50688
	s_waitcnt lgkmcnt(5)
	v_mfma_f32_32x32x16_bf16 v[96:111], v[218:221], v[0:3], 0
	ds_read_b128 v[218:221], v196 offset:32
	s_waitcnt lgkmcnt(5)
	v_mfma_f32_32x32x16_bf16 v[112:127], v[222:225], v[0:3], 0
	ds_read_b128 v[222:225], v196 offset:16928
	s_waitcnt lgkmcnt(5)
	v_mfma_f32_32x32x16_bf16 v[128:143], v[226:229], v[0:3], 0
	ds_read_b128 v[226:229], v196 offset:33824
	s_waitcnt lgkmcnt(5)
	v_mfma_f32_32x32x16_bf16 v[144:159], v[230:233], v[0:3], 0
	ds_read_b128 v[230:233], v196 offset:50720
	s_waitcnt lgkmcnt(5)
	v_mfma_f32_32x32x16_bf16 v[160:175], v[210:213], v[0:3], 0
	ds_read_b128 v[210:213], v197 offset:32
	s_waitcnt lgkmcnt(5)
	v_mfma_f32_32x32x16_bf16 v[176:191], v[214:217], v[0:3], 0
	ds_read_b128 v[214:217], v197 offset:16928
	s_waitcnt lgkmcnt(5)
	v_mfma_f32_32x32x16_bf16 v[64:79], v[218:221], v[4:7], v[64:79]
	ds_read_b128 v[218:221], v197 offset:33824
	s_waitcnt lgkmcnt(5)
	v_mfma_f32_32x32x16_bf16 v[80:95], v[222:225], v[4:7], v[80:95]
	ds_read_b128 v[222:225], v197 offset:50720
	s_waitcnt lgkmcnt(5)
	v_mfma_f32_32x32x16_bf16 v[96:111], v[226:229], v[4:7], v[96:111]
	ds_read_b128 v[226:229], v196 offset:64
	s_waitcnt lgkmcnt(5)
	v_mfma_f32_32x32x16_bf16 v[112:127], v[230:233], v[4:7], v[112:127]
	ds_read_b128 v[230:233], v196 offset:16960
	s_waitcnt lgkmcnt(5)
	v_mfma_f32_32x32x16_bf16 v[128:143], v[210:213], v[4:7], v[128:143]
	ds_read_b128 v[210:213], v196 offset:33856
	s_waitcnt lgkmcnt(5)
	v_mfma_f32_32x32x16_bf16 v[144:159], v[214:217], v[4:7], v[144:159]
	ds_read_b128 v[214:217], v196 offset:50752
	s_waitcnt lgkmcnt(5)
	v_mfma_f32_32x32x16_bf16 v[160:175], v[218:221], v[4:7], v[160:175]
	ds_read_b128 v[218:221], v197 offset:64
	s_waitcnt lgkmcnt(5)
	v_mfma_f32_32x32x16_bf16 v[176:191], v[222:225], v[4:7], v[176:191]
	ds_read_b128 v[222:225], v197 offset:16960
	global_load_dwordx4 v[0:3], v195, s[76:77]
	s_waitcnt lgkmcnt(5)
	v_mfma_f32_32x32x16_bf16 v[64:79], v[226:229], v[8:11], v[64:79]
	ds_read_b128 v[226:229], v197 offset:33856
	s_waitcnt lgkmcnt(5)
	v_mfma_f32_32x32x16_bf16 v[80:95], v[230:233], v[8:11], v[80:95]
	ds_read_b128 v[230:233], v197 offset:50752
	s_waitcnt lgkmcnt(5)
	v_mfma_f32_32x32x16_bf16 v[96:111], v[210:213], v[8:11], v[96:111]
	ds_read_b128 v[210:213], v196 offset:96
	s_waitcnt lgkmcnt(5)
	v_mfma_f32_32x32x16_bf16 v[112:127], v[214:217], v[8:11], v[112:127]
	ds_read_b128 v[214:217], v196 offset:16992
	s_waitcnt lgkmcnt(5)
	v_mfma_f32_32x32x16_bf16 v[128:143], v[218:221], v[8:11], v[128:143]
	ds_read_b128 v[218:221], v196 offset:33888
	s_waitcnt lgkmcnt(5)
	v_mfma_f32_32x32x16_bf16 v[144:159], v[222:225], v[8:11], v[144:159]
	ds_read_b128 v[222:225], v196 offset:50784
	s_waitcnt lgkmcnt(5)
	v_mfma_f32_32x32x16_bf16 v[160:175], v[226:229], v[8:11], v[160:175]
	ds_read_b128 v[226:229], v197 offset:96
	s_waitcnt lgkmcnt(5)
	v_mfma_f32_32x32x16_bf16 v[176:191], v[230:233], v[8:11], v[176:191]
	ds_read_b128 v[230:233], v197 offset:16992
	global_load_dwordx4 v[4:7], v195, s[76:77] offset:32
	s_waitcnt lgkmcnt(5)
	v_mfma_f32_32x32x16_bf16 v[64:79], v[210:213], v[12:15], v[64:79]
	ds_read_b128 v[210:213], v197 offset:33888
	s_waitcnt lgkmcnt(5)
	v_mfma_f32_32x32x16_bf16 v[80:95], v[214:217], v[12:15], v[80:95]
	ds_read_b128 v[214:217], v197 offset:50784
	s_waitcnt lgkmcnt(5)
	v_mfma_f32_32x32x16_bf16 v[96:111], v[218:221], v[12:15], v[96:111]
	ds_read_b128 v[218:221], v196 offset:128
	s_waitcnt lgkmcnt(5)
	v_mfma_f32_32x32x16_bf16 v[112:127], v[222:225], v[12:15], v[112:127]
	ds_read_b128 v[222:225], v196 offset:17024
	s_waitcnt lgkmcnt(5)
	v_mfma_f32_32x32x16_bf16 v[128:143], v[226:229], v[12:15], v[128:143]
	ds_read_b128 v[226:229], v196 offset:33920
	s_waitcnt lgkmcnt(5)
	v_mfma_f32_32x32x16_bf16 v[144:159], v[230:233], v[12:15], v[144:159]
	ds_read_b128 v[230:233], v196 offset:50816
	s_waitcnt lgkmcnt(5)
	v_mfma_f32_32x32x16_bf16 v[160:175], v[210:213], v[12:15], v[160:175]
	ds_read_b128 v[210:213], v197 offset:128
	s_waitcnt lgkmcnt(5)
	v_mfma_f32_32x32x16_bf16 v[176:191], v[214:217], v[12:15], v[176:191]
	ds_read_b128 v[214:217], v197 offset:17024
	global_load_dwordx4 v[8:11], v195, s[76:77] offset:64
	s_waitcnt lgkmcnt(5)
	v_mfma_f32_32x32x16_bf16 v[64:79], v[218:221], v[16:19], v[64:79]
	ds_read_b128 v[218:221], v197 offset:33920
	s_waitcnt lgkmcnt(5)
	v_mfma_f32_32x32x16_bf16 v[80:95], v[222:225], v[16:19], v[80:95]
	ds_read_b128 v[222:225], v197 offset:50816
	s_waitcnt lgkmcnt(5)
	v_mfma_f32_32x32x16_bf16 v[96:111], v[226:229], v[16:19], v[96:111]
	ds_read_b128 v[226:229], v196 offset:160
	s_waitcnt lgkmcnt(5)
	v_mfma_f32_32x32x16_bf16 v[112:127], v[230:233], v[16:19], v[112:127]
	ds_read_b128 v[230:233], v196 offset:17056
	s_waitcnt lgkmcnt(5)
	v_mfma_f32_32x32x16_bf16 v[128:143], v[210:213], v[16:19], v[128:143]
	ds_read_b128 v[210:213], v196 offset:33952
	s_waitcnt lgkmcnt(5)
	v_mfma_f32_32x32x16_bf16 v[144:159], v[214:217], v[16:19], v[144:159]
	ds_read_b128 v[214:217], v196 offset:50848
	s_waitcnt lgkmcnt(5)
	v_mfma_f32_32x32x16_bf16 v[160:175], v[218:221], v[16:19], v[160:175]
	ds_read_b128 v[218:221], v197 offset:160
	s_waitcnt lgkmcnt(5)
	v_mfma_f32_32x32x16_bf16 v[176:191], v[222:225], v[16:19], v[176:191]
	ds_read_b128 v[222:225], v197 offset:17056
	global_load_dwordx4 v[12:15], v195, s[76:77] offset:96
	s_waitcnt lgkmcnt(5)
	v_mfma_f32_32x32x16_bf16 v[64:79], v[226:229], v[20:23], v[64:79]
	ds_read_b128 v[226:229], v197 offset:33952
	s_waitcnt lgkmcnt(5)
	v_mfma_f32_32x32x16_bf16 v[80:95], v[230:233], v[20:23], v[80:95]
	ds_read_b128 v[230:233], v197 offset:50848
	s_waitcnt lgkmcnt(5)
	v_mfma_f32_32x32x16_bf16 v[96:111], v[210:213], v[20:23], v[96:111]
	ds_read_b128 v[210:213], v196 offset:192
	s_waitcnt lgkmcnt(5)
	v_mfma_f32_32x32x16_bf16 v[112:127], v[214:217], v[20:23], v[112:127]
	ds_read_b128 v[214:217], v196 offset:17088
	s_waitcnt lgkmcnt(5)
	v_mfma_f32_32x32x16_bf16 v[128:143], v[218:221], v[20:23], v[128:143]
	ds_read_b128 v[218:221], v196 offset:33984
	s_waitcnt lgkmcnt(5)
	v_mfma_f32_32x32x16_bf16 v[144:159], v[222:225], v[20:23], v[144:159]
	ds_read_b128 v[222:225], v196 offset:50880
	s_waitcnt lgkmcnt(5)
	v_mfma_f32_32x32x16_bf16 v[160:175], v[226:229], v[20:23], v[160:175]
	ds_read_b128 v[226:229], v197 offset:192
	s_waitcnt lgkmcnt(5)
	v_mfma_f32_32x32x16_bf16 v[176:191], v[230:233], v[20:23], v[176:191]
	ds_read_b128 v[230:233], v197 offset:17088
	global_load_dwordx4 v[16:19], v195, s[76:77] offset:128
	s_waitcnt lgkmcnt(5)
	v_mfma_f32_32x32x16_bf16 v[64:79], v[210:213], v[24:27], v[64:79]
	ds_read_b128 v[210:213], v197 offset:33984
	s_waitcnt lgkmcnt(5)
	v_mfma_f32_32x32x16_bf16 v[80:95], v[214:217], v[24:27], v[80:95]
	ds_read_b128 v[214:217], v197 offset:50880
	s_waitcnt lgkmcnt(5)
	v_mfma_f32_32x32x16_bf16 v[96:111], v[218:221], v[24:27], v[96:111]
	ds_read_b128 v[218:221], v196 offset:224
	s_waitcnt lgkmcnt(5)
	v_mfma_f32_32x32x16_bf16 v[112:127], v[222:225], v[24:27], v[112:127]
	ds_read_b128 v[222:225], v196 offset:17120
	s_waitcnt lgkmcnt(5)
	v_mfma_f32_32x32x16_bf16 v[128:143], v[226:229], v[24:27], v[128:143]
	ds_read_b128 v[226:229], v196 offset:34016
	s_waitcnt lgkmcnt(5)
	v_mfma_f32_32x32x16_bf16 v[144:159], v[230:233], v[24:27], v[144:159]
	ds_read_b128 v[230:233], v196 offset:50912
	s_waitcnt lgkmcnt(5)
	v_mfma_f32_32x32x16_bf16 v[160:175], v[210:213], v[24:27], v[160:175]
	ds_read_b128 v[210:213], v197 offset:224
	s_waitcnt lgkmcnt(5)
	v_mfma_f32_32x32x16_bf16 v[176:191], v[214:217], v[24:27], v[176:191]
	ds_read_b128 v[214:217], v197 offset:17120
	global_load_dwordx4 v[20:23], v195, s[76:77] offset:160
	s_waitcnt lgkmcnt(5)
	v_mfma_f32_32x32x16_bf16 v[64:79], v[218:221], v[28:31], v[64:79]
	ds_read_b128 v[218:221], v197 offset:34016
	s_waitcnt lgkmcnt(5)
	v_mfma_f32_32x32x16_bf16 v[80:95], v[222:225], v[28:31], v[80:95]
	ds_read_b128 v[222:225], v197 offset:50912
	s_waitcnt lgkmcnt(5)
	v_mfma_f32_32x32x16_bf16 v[96:111], v[226:229], v[28:31], v[96:111]
	ds_read_b128 v[226:229], v196 offset:256
	s_waitcnt lgkmcnt(5)
	v_mfma_f32_32x32x16_bf16 v[112:127], v[230:233], v[28:31], v[112:127]
	ds_read_b128 v[230:233], v196 offset:17152
	s_waitcnt lgkmcnt(5)
	v_mfma_f32_32x32x16_bf16 v[128:143], v[210:213], v[28:31], v[128:143]
	ds_read_b128 v[210:213], v196 offset:34048
	s_waitcnt lgkmcnt(5)
	v_mfma_f32_32x32x16_bf16 v[144:159], v[214:217], v[28:31], v[144:159]
	ds_read_b128 v[214:217], v196 offset:50944
	s_waitcnt lgkmcnt(5)
	v_mfma_f32_32x32x16_bf16 v[160:175], v[218:221], v[28:31], v[160:175]
	ds_read_b128 v[218:221], v197 offset:256
	s_waitcnt lgkmcnt(5)
	v_mfma_f32_32x32x16_bf16 v[176:191], v[222:225], v[28:31], v[176:191]
	ds_read_b128 v[222:225], v197 offset:17152
	global_load_dwordx4 v[24:27], v195, s[76:77] offset:192
	s_waitcnt lgkmcnt(5)
	v_mfma_f32_32x32x16_bf16 v[64:79], v[226:229], v[32:35], v[64:79]
	ds_read_b128 v[226:229], v197 offset:34048
	s_waitcnt lgkmcnt(5)
	v_mfma_f32_32x32x16_bf16 v[80:95], v[230:233], v[32:35], v[80:95]
	ds_read_b128 v[230:233], v197 offset:50944
	s_waitcnt lgkmcnt(5)
	v_mfma_f32_32x32x16_bf16 v[96:111], v[210:213], v[32:35], v[96:111]
	ds_read_b128 v[210:213], v196 offset:288
	s_waitcnt lgkmcnt(5)
	v_mfma_f32_32x32x16_bf16 v[112:127], v[214:217], v[32:35], v[112:127]
	ds_read_b128 v[214:217], v196 offset:17184
	s_waitcnt lgkmcnt(5)
	v_mfma_f32_32x32x16_bf16 v[128:143], v[218:221], v[32:35], v[128:143]
	ds_read_b128 v[218:221], v196 offset:34080
	s_waitcnt lgkmcnt(5)
	v_mfma_f32_32x32x16_bf16 v[144:159], v[222:225], v[32:35], v[144:159]
	ds_read_b128 v[222:225], v196 offset:50976
	s_waitcnt lgkmcnt(5)
	v_mfma_f32_32x32x16_bf16 v[160:175], v[226:229], v[32:35], v[160:175]
	ds_read_b128 v[226:229], v197 offset:288
	s_waitcnt lgkmcnt(5)
	v_mfma_f32_32x32x16_bf16 v[176:191], v[230:233], v[32:35], v[176:191]
	ds_read_b128 v[230:233], v197 offset:17184
	global_load_dwordx4 v[28:31], v195, s[76:77] offset:224
	s_waitcnt lgkmcnt(5)
	v_mfma_f32_32x32x16_bf16 v[64:79], v[210:213], v[36:39], v[64:79]
	ds_read_b128 v[210:213], v197 offset:34080
	s_waitcnt lgkmcnt(5)
	v_mfma_f32_32x32x16_bf16 v[80:95], v[214:217], v[36:39], v[80:95]
	ds_read_b128 v[214:217], v197 offset:50976
	s_waitcnt lgkmcnt(5)
	v_mfma_f32_32x32x16_bf16 v[96:111], v[218:221], v[36:39], v[96:111]
	ds_read_b128 v[218:221], v196 offset:320
	s_waitcnt lgkmcnt(5)
	v_mfma_f32_32x32x16_bf16 v[112:127], v[222:225], v[36:39], v[112:127]
	ds_read_b128 v[222:225], v196 offset:17216
	s_waitcnt lgkmcnt(5)
	v_mfma_f32_32x32x16_bf16 v[128:143], v[226:229], v[36:39], v[128:143]
	ds_read_b128 v[226:229], v196 offset:34112
	s_waitcnt lgkmcnt(5)
	v_mfma_f32_32x32x16_bf16 v[144:159], v[230:233], v[36:39], v[144:159]
	ds_read_b128 v[230:233], v196 offset:51008
	s_waitcnt lgkmcnt(5)
	v_mfma_f32_32x32x16_bf16 v[160:175], v[210:213], v[36:39], v[160:175]
	ds_read_b128 v[210:213], v197 offset:320
	s_waitcnt lgkmcnt(5)
	v_mfma_f32_32x32x16_bf16 v[176:191], v[214:217], v[36:39], v[176:191]
	ds_read_b128 v[214:217], v197 offset:17216
	global_load_dwordx4 v[32:35], v195, s[76:77] offset:256
	s_waitcnt lgkmcnt(5)
	v_mfma_f32_32x32x16_bf16 v[64:79], v[218:221], v[40:43], v[64:79]
	ds_read_b128 v[218:221], v197 offset:34112
	s_waitcnt lgkmcnt(5)
	v_mfma_f32_32x32x16_bf16 v[80:95], v[222:225], v[40:43], v[80:95]
	ds_read_b128 v[222:225], v197 offset:51008
	s_waitcnt lgkmcnt(5)
	v_mfma_f32_32x32x16_bf16 v[96:111], v[226:229], v[40:43], v[96:111]
	ds_read_b128 v[226:229], v196 offset:352
	s_waitcnt lgkmcnt(5)
	v_mfma_f32_32x32x16_bf16 v[112:127], v[230:233], v[40:43], v[112:127]
	ds_read_b128 v[230:233], v196 offset:17248
	s_waitcnt lgkmcnt(5)
	v_mfma_f32_32x32x16_bf16 v[128:143], v[210:213], v[40:43], v[128:143]
	ds_read_b128 v[210:213], v196 offset:34144
	s_waitcnt lgkmcnt(5)
	v_mfma_f32_32x32x16_bf16 v[144:159], v[214:217], v[40:43], v[144:159]
	ds_read_b128 v[214:217], v196 offset:51040
	s_waitcnt lgkmcnt(5)
	v_mfma_f32_32x32x16_bf16 v[160:175], v[218:221], v[40:43], v[160:175]
	ds_read_b128 v[218:221], v197 offset:352
	s_waitcnt lgkmcnt(5)
	v_mfma_f32_32x32x16_bf16 v[176:191], v[222:225], v[40:43], v[176:191]
	ds_read_b128 v[222:225], v197 offset:17248
	global_load_dwordx4 v[36:39], v195, s[76:77] offset:288
	s_waitcnt lgkmcnt(5)
	v_mfma_f32_32x32x16_bf16 v[64:79], v[226:229], v[44:47], v[64:79]
	ds_read_b128 v[226:229], v197 offset:34144
	s_waitcnt lgkmcnt(5)
	v_mfma_f32_32x32x16_bf16 v[80:95], v[230:233], v[44:47], v[80:95]
	ds_read_b128 v[230:233], v197 offset:51040
	s_waitcnt lgkmcnt(5)
	v_mfma_f32_32x32x16_bf16 v[96:111], v[210:213], v[44:47], v[96:111]
	ds_read_b128 v[210:213], v196 offset:384
	s_waitcnt lgkmcnt(5)
	v_mfma_f32_32x32x16_bf16 v[112:127], v[214:217], v[44:47], v[112:127]
	ds_read_b128 v[214:217], v196 offset:17280
	s_waitcnt lgkmcnt(5)
	v_mfma_f32_32x32x16_bf16 v[128:143], v[218:221], v[44:47], v[128:143]
	ds_read_b128 v[218:221], v196 offset:34176
	s_waitcnt lgkmcnt(5)
	v_mfma_f32_32x32x16_bf16 v[144:159], v[222:225], v[44:47], v[144:159]
	ds_read_b128 v[222:225], v196 offset:51072
	s_waitcnt lgkmcnt(5)
	v_mfma_f32_32x32x16_bf16 v[160:175], v[226:229], v[44:47], v[160:175]
	ds_read_b128 v[226:229], v197 offset:384
	s_waitcnt lgkmcnt(5)
	v_mfma_f32_32x32x16_bf16 v[176:191], v[230:233], v[44:47], v[176:191]
	ds_read_b128 v[230:233], v197 offset:17280
	global_load_dwordx4 v[40:43], v195, s[76:77] offset:320
	s_waitcnt lgkmcnt(5)
	v_mfma_f32_32x32x16_bf16 v[64:79], v[210:213], v[48:51], v[64:79]
	ds_read_b128 v[210:213], v197 offset:34176
	s_waitcnt lgkmcnt(5)
	v_mfma_f32_32x32x16_bf16 v[80:95], v[214:217], v[48:51], v[80:95]
	ds_read_b128 v[214:217], v197 offset:51072
	s_waitcnt lgkmcnt(5)
	v_mfma_f32_32x32x16_bf16 v[96:111], v[218:221], v[48:51], v[96:111]
	ds_read_b128 v[218:221], v196 offset:416
	s_waitcnt lgkmcnt(5)
	v_mfma_f32_32x32x16_bf16 v[112:127], v[222:225], v[48:51], v[112:127]
	ds_read_b128 v[222:225], v196 offset:17312
	s_waitcnt lgkmcnt(5)
	v_mfma_f32_32x32x16_bf16 v[128:143], v[226:229], v[48:51], v[128:143]
	ds_read_b128 v[226:229], v196 offset:34208
	s_waitcnt lgkmcnt(5)
	v_mfma_f32_32x32x16_bf16 v[144:159], v[230:233], v[48:51], v[144:159]
	ds_read_b128 v[230:233], v196 offset:51104
	s_waitcnt lgkmcnt(5)
	v_mfma_f32_32x32x16_bf16 v[160:175], v[210:213], v[48:51], v[160:175]
	ds_read_b128 v[210:213], v197 offset:416
	s_waitcnt lgkmcnt(5)
	v_mfma_f32_32x32x16_bf16 v[176:191], v[214:217], v[48:51], v[176:191]
	ds_read_b128 v[214:217], v197 offset:17312
	global_load_dwordx4 v[44:47], v195, s[76:77] offset:352
	s_waitcnt lgkmcnt(5)
	v_mfma_f32_32x32x16_bf16 v[64:79], v[218:221], v[52:55], v[64:79]
	ds_read_b128 v[218:221], v197 offset:34208
	s_waitcnt lgkmcnt(5)
	v_mfma_f32_32x32x16_bf16 v[80:95], v[222:225], v[52:55], v[80:95]
	ds_read_b128 v[222:225], v197 offset:51104
	s_waitcnt lgkmcnt(5)
	v_mfma_f32_32x32x16_bf16 v[96:111], v[226:229], v[52:55], v[96:111]
	ds_read_b128 v[226:229], v196 offset:448
	s_waitcnt lgkmcnt(5)
	v_mfma_f32_32x32x16_bf16 v[112:127], v[230:233], v[52:55], v[112:127]
	ds_read_b128 v[230:233], v196 offset:17344
	s_waitcnt lgkmcnt(5)
	v_mfma_f32_32x32x16_bf16 v[128:143], v[210:213], v[52:55], v[128:143]
	ds_read_b128 v[210:213], v196 offset:34240
	s_waitcnt lgkmcnt(5)
	v_mfma_f32_32x32x16_bf16 v[144:159], v[214:217], v[52:55], v[144:159]
	ds_read_b128 v[214:217], v196 offset:51136
	s_waitcnt lgkmcnt(5)
	v_mfma_f32_32x32x16_bf16 v[160:175], v[218:221], v[52:55], v[160:175]
	ds_read_b128 v[218:221], v197 offset:448
	s_waitcnt lgkmcnt(5)
	v_mfma_f32_32x32x16_bf16 v[176:191], v[222:225], v[52:55], v[176:191]
	ds_read_b128 v[222:225], v197 offset:17344
	global_load_dwordx4 v[48:51], v195, s[76:77] offset:384
	s_waitcnt lgkmcnt(5)
	v_mfma_f32_32x32x16_bf16 v[64:79], v[226:229], v[56:59], v[64:79]
	ds_read_b128 v[226:229], v197 offset:34240
	s_waitcnt lgkmcnt(5)
	v_mfma_f32_32x32x16_bf16 v[80:95], v[230:233], v[56:59], v[80:95]
	ds_read_b128 v[230:233], v197 offset:51136
	s_waitcnt lgkmcnt(5)
	v_mfma_f32_32x32x16_bf16 v[96:111], v[210:213], v[56:59], v[96:111]
	ds_read_b128 v[210:213], v196 offset:480
	s_waitcnt lgkmcnt(5)
	v_mfma_f32_32x32x16_bf16 v[112:127], v[214:217], v[56:59], v[112:127]
	ds_read_b128 v[214:217], v196 offset:17376
	s_waitcnt lgkmcnt(5)
	v_mfma_f32_32x32x16_bf16 v[128:143], v[218:221], v[56:59], v[128:143]
	ds_read_b128 v[218:221], v196 offset:34272
	s_waitcnt lgkmcnt(5)
	v_mfma_f32_32x32x16_bf16 v[144:159], v[222:225], v[56:59], v[144:159]
	ds_read_b128 v[222:225], v196 offset:51168
	s_waitcnt lgkmcnt(5)
	v_mfma_f32_32x32x16_bf16 v[160:175], v[226:229], v[56:59], v[160:175]
	ds_read_b128 v[226:229], v197 offset:480
	s_waitcnt lgkmcnt(5)
	v_mfma_f32_32x32x16_bf16 v[176:191], v[230:233], v[56:59], v[176:191]
	ds_read_b128 v[230:233], v197 offset:17376
	global_load_dwordx4 v[52:55], v195, s[76:77] offset:416
	s_waitcnt lgkmcnt(5)
	v_mfma_f32_32x32x16_bf16 v[64:79], v[210:213], v[60:63], v[64:79]
	ds_read_b128 v[210:213], v197 offset:34272
	s_waitcnt lgkmcnt(5)
	v_mfma_f32_32x32x16_bf16 v[80:95], v[214:217], v[60:63], v[80:95]
	ds_read_b128 v[214:217], v197 offset:51168
	s_waitcnt lgkmcnt(5)
	v_mfma_f32_32x32x16_bf16 v[96:111], v[218:221], v[60:63], v[96:111]
	s_waitcnt lgkmcnt(4)
	v_mfma_f32_32x32x16_bf16 v[112:127], v[222:225], v[60:63], v[112:127]
	s_waitcnt lgkmcnt(3)
	v_mfma_f32_32x32x16_bf16 v[128:143], v[226:229], v[60:63], v[128:143]
	s_waitcnt lgkmcnt(2)
	v_mfma_f32_32x32x16_bf16 v[144:159], v[230:233], v[60:63], v[144:159]
	s_waitcnt lgkmcnt(1)
	v_mfma_f32_32x32x16_bf16 v[160:175], v[210:213], v[60:63], v[160:175]
	s_waitcnt lgkmcnt(0)
	v_mfma_f32_32x32x16_bf16 v[176:191], v[214:217], v[60:63], v[176:191]
	global_load_dwordx4 v[56:59], v195, s[76:77] offset:448
	global_load_dwordx4 v[60:63], v195, s[76:77] offset:480
	s_nop 7
	s_nop 3
	v_mul_f32_e32 v64, v64, v199
	v_mul_f32_e32 v65, v65, v199
	v_mul_f32_e32 v66, v66, v199
	v_mul_f32_e32 v67, v67, v199
	v_mul_f32_e32 v68, v68, v199
	v_mul_f32_e32 v69, v69, v199
	v_mul_f32_e32 v70, v70, v199
	v_mul_f32_e32 v71, v71, v199
	v_mul_f32_e32 v72, v72, v199
	v_mul_f32_e32 v73, v73, v199
	v_mul_f32_e32 v74, v74, v199
	v_mul_f32_e32 v75, v75, v199
	v_mul_f32_e32 v76, v76, v199
	v_mul_f32_e32 v77, v77, v199
	v_mul_f32_e32 v78, v78, v199
	v_mul_f32_e32 v79, v79, v199
	v_cvt_pk_bf16_f32 v64, v64, v65
	v_cvt_pk_bf16_f32 v65, v66, v67
	v_cvt_pk_bf16_f32 v66, v68, v69
	v_cvt_pk_bf16_f32 v67, v70, v71
	v_cvt_pk_bf16_f32 v68, v72, v73
	v_cvt_pk_bf16_f32 v69, v74, v75
	v_cvt_pk_bf16_f32 v70, v76, v77
	v_cvt_pk_bf16_f32 v71, v78, v79
	s_nop 1
	v_permlane32_swap_b32_e32 v64, v66
	v_permlane32_swap_b32_e32 v65, v67
	v_permlane32_swap_b32_e32 v68, v70
	v_permlane32_swap_b32_e32 v69, v71
	s_mov_b64 exec, s[62:63]
	global_store_dwordx4 v195, v[64:67], s[52:53]
	global_store_dwordx4 v195, v[68:71], s[52:53] offset:32
	s_mov_b64 exec, -1
	v_mul_f32_e32 v80, v80, v199
	v_mul_f32_e32 v81, v81, v199
	v_mul_f32_e32 v82, v82, v199
	v_mul_f32_e32 v83, v83, v199
	v_mul_f32_e32 v84, v84, v199
	v_mul_f32_e32 v85, v85, v199
	v_mul_f32_e32 v86, v86, v199
	v_mul_f32_e32 v87, v87, v199
	v_mul_f32_e32 v88, v88, v199
	v_mul_f32_e32 v89, v89, v199
	v_mul_f32_e32 v90, v90, v199
	v_mul_f32_e32 v91, v91, v199
	v_mul_f32_e32 v92, v92, v199
	v_mul_f32_e32 v93, v93, v199
	v_mul_f32_e32 v94, v94, v199
	v_mul_f32_e32 v95, v95, v199
	v_cvt_pk_bf16_f32 v80, v80, v81
	v_cvt_pk_bf16_f32 v81, v82, v83
	v_cvt_pk_bf16_f32 v82, v84, v85
	v_cvt_pk_bf16_f32 v83, v86, v87
	v_cvt_pk_bf16_f32 v84, v88, v89
	v_cvt_pk_bf16_f32 v85, v90, v91
	v_cvt_pk_bf16_f32 v86, v92, v93
	v_cvt_pk_bf16_f32 v87, v94, v95
	s_nop 1
	v_permlane32_swap_b32_e32 v80, v82
	v_permlane32_swap_b32_e32 v81, v83
	v_permlane32_swap_b32_e32 v84, v86
	v_permlane32_swap_b32_e32 v85, v87
	s_mov_b64 exec, s[62:63]
	global_store_dwordx4 v195, v[80:83], s[52:53] offset:64
	global_store_dwordx4 v195, v[84:87], s[52:53] offset:96
	s_mov_b64 exec, -1
	v_mul_f32_e32 v96, v96, v199
	v_mul_f32_e32 v97, v97, v199
	v_mul_f32_e32 v98, v98, v199
	v_mul_f32_e32 v99, v99, v199
	v_mul_f32_e32 v100, v100, v199
	v_mul_f32_e32 v101, v101, v199
	v_mul_f32_e32 v102, v102, v199
	v_mul_f32_e32 v103, v103, v199
	v_mul_f32_e32 v104, v104, v199
	v_mul_f32_e32 v105, v105, v199
	v_mul_f32_e32 v106, v106, v199
	v_mul_f32_e32 v107, v107, v199
	v_mul_f32_e32 v108, v108, v199
	v_mul_f32_e32 v109, v109, v199
	v_mul_f32_e32 v110, v110, v199
	v_mul_f32_e32 v111, v111, v199
	v_cvt_pk_bf16_f32 v96, v96, v97
	v_cvt_pk_bf16_f32 v97, v98, v99
	v_cvt_pk_bf16_f32 v98, v100, v101
	v_cvt_pk_bf16_f32 v99, v102, v103
	v_cvt_pk_bf16_f32 v100, v104, v105
	v_cvt_pk_bf16_f32 v101, v106, v107
	v_cvt_pk_bf16_f32 v102, v108, v109
	v_cvt_pk_bf16_f32 v103, v110, v111
	s_nop 1
	v_permlane32_swap_b32_e32 v96, v98
	v_permlane32_swap_b32_e32 v97, v99
	v_permlane32_swap_b32_e32 v100, v102
	v_permlane32_swap_b32_e32 v101, v103
	s_mov_b64 exec, s[62:63]
	global_store_dwordx4 v195, v[96:99], s[52:53] offset:128
	global_store_dwordx4 v195, v[100:103], s[52:53] offset:160
	s_mov_b64 exec, -1
	v_mul_f32_e32 v112, v112, v199
	v_mul_f32_e32 v113, v113, v199
	v_mul_f32_e32 v114, v114, v199
	v_mul_f32_e32 v115, v115, v199
	v_mul_f32_e32 v116, v116, v199
	v_mul_f32_e32 v117, v117, v199
	v_mul_f32_e32 v118, v118, v199
	v_mul_f32_e32 v119, v119, v199
	v_mul_f32_e32 v120, v120, v199
	v_mul_f32_e32 v121, v121, v199
	v_mul_f32_e32 v122, v122, v199
	v_mul_f32_e32 v123, v123, v199
	v_mul_f32_e32 v124, v124, v199
	v_mul_f32_e32 v125, v125, v199
	v_mul_f32_e32 v126, v126, v199
	v_mul_f32_e32 v127, v127, v199
	v_cvt_pk_bf16_f32 v112, v112, v113
	v_cvt_pk_bf16_f32 v113, v114, v115
	v_cvt_pk_bf16_f32 v114, v116, v117
	v_cvt_pk_bf16_f32 v115, v118, v119
	v_cvt_pk_bf16_f32 v116, v120, v121
	v_cvt_pk_bf16_f32 v117, v122, v123
	v_cvt_pk_bf16_f32 v118, v124, v125
	v_cvt_pk_bf16_f32 v119, v126, v127
	s_nop 1
	v_permlane32_swap_b32_e32 v112, v114
	v_permlane32_swap_b32_e32 v113, v115
	v_permlane32_swap_b32_e32 v116, v118
	v_permlane32_swap_b32_e32 v117, v119
	s_mov_b64 exec, s[62:63]
	global_store_dwordx4 v195, v[112:115], s[52:53] offset:192
	global_store_dwordx4 v195, v[116:119], s[52:53] offset:224
	s_mov_b64 exec, -1
	v_mul_f32_e32 v128, v128, v199
	v_mul_f32_e32 v129, v129, v199
	v_mul_f32_e32 v130, v130, v199
	v_mul_f32_e32 v131, v131, v199
	v_mul_f32_e32 v132, v132, v199
	v_mul_f32_e32 v133, v133, v199
	v_mul_f32_e32 v134, v134, v199
	v_mul_f32_e32 v135, v135, v199
	v_mul_f32_e32 v136, v136, v199
	v_mul_f32_e32 v137, v137, v199
	v_mul_f32_e32 v138, v138, v199
	v_mul_f32_e32 v139, v139, v199
	v_mul_f32_e32 v140, v140, v199
	v_mul_f32_e32 v141, v141, v199
	v_mul_f32_e32 v142, v142, v199
	v_mul_f32_e32 v143, v143, v199
	v_cvt_pk_bf16_f32 v128, v128, v129
	v_cvt_pk_bf16_f32 v129, v130, v131
	v_cvt_pk_bf16_f32 v130, v132, v133
	v_cvt_pk_bf16_f32 v131, v134, v135
	v_cvt_pk_bf16_f32 v132, v136, v137
	v_cvt_pk_bf16_f32 v133, v138, v139
	v_cvt_pk_bf16_f32 v134, v140, v141
	v_cvt_pk_bf16_f32 v135, v142, v143
	s_nop 1
	v_permlane32_swap_b32_e32 v128, v130
	v_permlane32_swap_b32_e32 v129, v131
	v_permlane32_swap_b32_e32 v132, v134
	v_permlane32_swap_b32_e32 v133, v135
	s_mov_b64 exec, s[62:63]
	global_store_dwordx4 v195, v[128:131], s[52:53] offset:256
	global_store_dwordx4 v195, v[132:135], s[52:53] offset:288
	s_mov_b64 exec, -1
	v_mul_f32_e32 v144, v144, v199
	v_mul_f32_e32 v145, v145, v199
	v_mul_f32_e32 v146, v146, v199
	v_mul_f32_e32 v147, v147, v199
	v_mul_f32_e32 v148, v148, v199
	v_mul_f32_e32 v149, v149, v199
	v_mul_f32_e32 v150, v150, v199
	v_mul_f32_e32 v151, v151, v199
	v_mul_f32_e32 v152, v152, v199
	v_mul_f32_e32 v153, v153, v199
	v_mul_f32_e32 v154, v154, v199
	v_mul_f32_e32 v155, v155, v199
	v_mul_f32_e32 v156, v156, v199
	v_mul_f32_e32 v157, v157, v199
	v_mul_f32_e32 v158, v158, v199
	v_mul_f32_e32 v159, v159, v199
	v_cvt_pk_bf16_f32 v144, v144, v145
	v_cvt_pk_bf16_f32 v145, v146, v147
	v_cvt_pk_bf16_f32 v146, v148, v149
	v_cvt_pk_bf16_f32 v147, v150, v151
	v_cvt_pk_bf16_f32 v148, v152, v153
	v_cvt_pk_bf16_f32 v149, v154, v155
	v_cvt_pk_bf16_f32 v150, v156, v157
	v_cvt_pk_bf16_f32 v151, v158, v159
	s_nop 1
	v_permlane32_swap_b32_e32 v144, v146
	v_permlane32_swap_b32_e32 v145, v147
	v_permlane32_swap_b32_e32 v148, v150
	v_permlane32_swap_b32_e32 v149, v151
	s_mov_b64 exec, s[62:63]
	global_store_dwordx4 v195, v[144:147], s[52:53] offset:320
	global_store_dwordx4 v195, v[148:151], s[52:53] offset:352
	s_mov_b64 exec, -1
	v_mul_f32_e32 v160, v160, v199
	v_mul_f32_e32 v161, v161, v199
	v_mul_f32_e32 v162, v162, v199
	v_mul_f32_e32 v163, v163, v199
	v_mul_f32_e32 v164, v164, v199
	v_mul_f32_e32 v165, v165, v199
	v_mul_f32_e32 v166, v166, v199
	v_mul_f32_e32 v167, v167, v199
	v_mul_f32_e32 v168, v168, v199
	v_mul_f32_e32 v169, v169, v199
	v_mul_f32_e32 v170, v170, v199
	v_mul_f32_e32 v171, v171, v199
	v_mul_f32_e32 v172, v172, v199
	v_mul_f32_e32 v173, v173, v199
	v_mul_f32_e32 v174, v174, v199
	v_mul_f32_e32 v175, v175, v199
	v_cvt_pk_bf16_f32 v160, v160, v161
	v_cvt_pk_bf16_f32 v161, v162, v163
	v_cvt_pk_bf16_f32 v162, v164, v165
	v_cvt_pk_bf16_f32 v163, v166, v167
	v_cvt_pk_bf16_f32 v164, v168, v169
	v_cvt_pk_bf16_f32 v165, v170, v171
	v_cvt_pk_bf16_f32 v166, v172, v173
	v_cvt_pk_bf16_f32 v167, v174, v175
	s_nop 1
	v_permlane32_swap_b32_e32 v160, v162
	v_permlane32_swap_b32_e32 v161, v163
	v_permlane32_swap_b32_e32 v164, v166
	v_permlane32_swap_b32_e32 v165, v167
	s_mov_b64 exec, s[62:63]
	global_store_dwordx4 v195, v[160:163], s[52:53] offset:384
	global_store_dwordx4 v195, v[164:167], s[52:53] offset:416
	s_mov_b64 exec, -1
	v_mul_f32_e32 v176, v176, v199
	v_mul_f32_e32 v177, v177, v199
	v_mul_f32_e32 v178, v178, v199
	v_mul_f32_e32 v179, v179, v199
	v_mul_f32_e32 v180, v180, v199
	v_mul_f32_e32 v181, v181, v199
	v_mul_f32_e32 v182, v182, v199
	v_mul_f32_e32 v183, v183, v199
	v_mul_f32_e32 v184, v184, v199
	v_mul_f32_e32 v185, v185, v199
	v_mul_f32_e32 v186, v186, v199
	v_mul_f32_e32 v187, v187, v199
	v_mul_f32_e32 v188, v188, v199
	v_mul_f32_e32 v189, v189, v199
	v_mul_f32_e32 v190, v190, v199
	v_mul_f32_e32 v191, v191, v199
	v_cvt_pk_bf16_f32 v176, v176, v177
	v_cvt_pk_bf16_f32 v177, v178, v179
	v_cvt_pk_bf16_f32 v178, v180, v181
	v_cvt_pk_bf16_f32 v179, v182, v183
	v_cvt_pk_bf16_f32 v180, v184, v185
	v_cvt_pk_bf16_f32 v181, v186, v187
	v_cvt_pk_bf16_f32 v182, v188, v189
	v_cvt_pk_bf16_f32 v183, v190, v191
	s_nop 1
	v_permlane32_swap_b32_e32 v176, v178
	v_permlane32_swap_b32_e32 v177, v179
	v_permlane32_swap_b32_e32 v180, v182
	v_permlane32_swap_b32_e32 v181, v183
	s_mov_b64 exec, s[62:63]
	global_store_dwordx4 v195, v[176:179], s[52:53] offset:448
	global_store_dwordx4 v195, v[180:183], s[52:53] offset:480
	s_mov_b64 exec, -1
	s_sub_u32 s58, s58, 1
	s_add_u32 s50, s50, 0x80000
	s_addc_u32 s51, s51, 0
	s_add_u32 s52, s52, 0x80000
	s_addc_u32 s53, s53, 0
	s_add_u32 s76, s76, 0x80000
	s_addc_u32 s77, s77, 0
	s_cmp_lg_u32 s58, 0
	s_cbranch_scc1 .Lxa_tile
	s_cmp_lg_u32 s59, 0
	s_cbranch_scc1 .Lxa_done
	s_cmp_ge_u32 s2, 64
	s_cbranch_scc1 .Lxa_done
	s_mov_b32 s59, 1
	s_mov_b32 s58, 1
	s_lshr_b32 s11, s2, 2
	s_and_b32 s12, s2, 3
	s_lshl_b32 s13, s12, 9
	s_lshl_b32 s18, s11, 4
	s_add_u32 s18, s18, 0x10000
	s_lshl_b32 s19, s11, 8
	s_add_u32 s19, s19, 0x2000
	s_waitcnt vmcnt(0)
	v_lshlrev_b32_e32 v195, 11, v250
	v_lshl_add_u32 v195, v251, 4, v195
	v_and_b32_e32 v200, 0x3df, v206
	v_cmp_gt_u32_e64 s[62:63], 16, v200
	s_branch .Lxa_unit
.Lxa_done:
	s_waitcnt vmcnt(0)
.LBB0_1212:
	s_waitcnt lgkmcnt(0)
	s_barrier
	s_waitcnt vmcnt(0) lgkmcnt(0)
	s_barrier
	s_waitcnt vmcnt(0)
	s_barrier
	s_and_saveexec_b64 s[10:11], s[4:5]
	s_cbranch_execz .LBB0_1264
	s_add_i32 s12, 0, 0x27ff0
	v_mov_b32_e32 v0, s12
	s_waitcnt vmcnt(0) expcnt(0) lgkmcnt(0)
	ds_read_b32 v2, v0
	s_add_i32 s12, 0, 0x27ff4
	v_mov_b32_e32 v0, s12
	ds_read_b32 v0, v0
	s_waitcnt lgkmcnt(1)
	v_cmp_ne_u32_e32 vcc, 0, v2
	s_cbranch_vccnz .LBB0_1228
	s_add_u32 s12, s38, 0x4200
	s_addc_u32 s13, s39, 0
	s_add_u32 s18, s38, 0x4400
	s_addc_u32 s19, s39, 0
	s_add_u32 s20, s38, 0x4500
	s_addc_u32 s21, s39, 0
	s_add_u32 s24, s38, 0x4600
	s_addc_u32 s25, s39, 0
	s_add_u32 s26, s38, 0x4700
	s_addc_u32 s27, s39, 0
	s_add_u32 s28, s38, 0x4800
	s_addc_u32 s29, s39, 0
	s_add_u32 s30, s38, 0x4900
	s_addc_u32 s31, s39, 0
	s_add_u32 s40, s38, 0x4a00
	s_addc_u32 s41, s39, 0
	s_add_u32 s42, s38, 0x4b00
	s_addc_u32 s43, s39, 0
	s_add_u32 s50, s38, 0x4c00
	s_addc_u32 s51, s39, 0
	s_add_u32 s52, s38, 0x4d00
	s_addc_u32 s53, s39, 0
	s_add_u32 s54, s38, 0x4e00
	s_addc_u32 s55, s39, 0
	s_add_u32 s56, s38, 0x4f00
	s_addc_u32 s57, s39, 0
	s_add_u32 s58, s38, 0x5000
	s_addc_u32 s59, s39, 0
	s_add_u32 s60, s38, 0x5100
	s_addc_u32 s61, s39, 0
	s_add_u32 s62, s38, 0x5200
	s_addc_u32 s63, s39, 0
	s_mul_i32 s35, s47, s85
	s_add_u32 s64, s38, 0x5300
	s_mul_i32 s35, s35, s46
	s_addc_u32 s65, s39, 0
	s_mov_b32 s72, 1
	v_mov_b32_e32 v16, 0
	s_branch .LBB0_1216
